# speedup vs baseline: 1.0044x; 1.0044x over previous
; DEV void sb_item(const Params& p, int item, unsigned char* smem) {
;   const int qb = 63 - (item & 63), h = (item >> 6) & 3, b = item >> 8;
;   const int tid = tidx(), w = tid >> 6, lane = tid & 63, fr = lane & 15, fq = lane >> 4;
;   u16* sP = (u16*)(smem + L_PW) + w * RW * VS;
;   int* flags = (int*)(smem + L_FLAG);
;   const u16* base = p.proj + (size_t)b * SEQ * DIN;
;   const int q0 = qb * QR + w * RW;
;   bf16x8 qf[MT][4];
;   load_qfrags(base + (size_t)q0 * DIN + C_SQ + h * 128, qf, fr, fq);
;   f32x4 o[MT][8];
;   float run[MT][4];
; #pragma unroll
;   for (int mt = 0; mt < MT; ++mt) {
; #pragma unroll
;     for (int nt = 0; nt < 8; ++nt) o[mt][nt] = (f32x4){0.f, 0.f, 0.f, 0.f};
; #pragma unroll
;     for (int j = 0; j < 4; ++j) run[mt][j] = 0.f;
;   }
;   const float scale = 0.08838834764831845f;
;   uint4 kq0, kq1, vq0, vq1;
;   {
;     const int kt0 = (qb * QR + QR - 1) / 64;
;     kv_load(base + (size_t)(kt0 * 64) * DIN + C_SK + h * 128, base + (size_t)(kt0 * 64) * DIN + C_SV + h * 128, kq0, kq1, vq0, vq1, tid);
;   }
;   __syncthreads();
;   int it = 0;
;     ...
;     u16* sK = (u16*)(smem + L_K + (it & 1) * KB_B); u16* sVt = (u16*)(smem + L_VT + (it & 1) * VB_B);
;     kv_store(kq0, kq1, vq0, vq1, sK, sVt, tid);
;     if (kt > 0) kv_load(base + (size_t)((kt - 1) * 64) * DIN + C_SK + h * 128, base + (size_t)((kt - 1) * 64) * DIN + C_SV + h * 128, kq0, kq1, vq0, vq1, tid);
;     __syncthreads();
.LBB0_422:
	s_ashr_i32 s92, s34, 8
	v_readfirstlane_b32 s0, v160
	s_andn2_b32 s0, s0, 63
	s_mul_i32 s1, s92, 0x5000000
	v_or_b32_e32 v51, s0, v161
	s_mul_hi_i32 s0, s92, 0x5000000
	s_add_u32 s12, s76, s1
	s_addc_u32 s13, s77, s0
	s_not_b32 s0, s34
	s_lshl_b32 s0, s0, 7
	s_and_b32 s14, s0, 0x1f80
	v_ashrrev_i32_e32 v49, 6, v51
	v_lshl_add_u32 v80, v49, 4, s14
	v_mov_b64_e32 v[0:1], s[12:13]
	v_mad_i64_i32 v[0:1], s[0:1], v80, s88, v[0:1]
	s_lshl_b32 s0, s34, 1
	s_lshr_b32 s35, s14, 6
	s_and_b32 s0, s0, 0x180
	s_or_b32 s4, s35, 1
	s_lshl_b32 s18, s0, 1
	s_mul_i32 s0, s4, 0xa0000
	s_add_u32 s0, s12, s0
	s_addc_u32 s1, s13, 0
	v_and_b32_e32 v92, 15, v51
	s_add_u32 s0, s0, s18
	v_mul_u32_u24_e32 v2, 0x1400, v92
	s_addc_u32 s1, s1, 0
	v_lshlrev_b32_e32 v6, 3, v51
	v_and_b32_e32 v48, 63, v51
	v_lshl_add_u64 v[0:1], v[0:1], 0, s[18:19]
	v_lshlrev_b32_e32 v128, 1, v2
	s_add_u32 s6, s0, 0x1400
	v_and_b32_e32 v6, 0x78, v6
	v_lshl_add_u64 v[0:1], v[0:1], 0, v[128:129]
	s_addc_u32 s7, s1, 0
	v_add_u32_e32 v10, 0x200, v51
	v_lshlrev_b32_e32 v128, 1, v6
	v_mul_u32_u24_e32 v6, 0x1400, v48
	v_ashrrev_i32_e32 v8, 3, v51
	v_ashrrev_i32_e32 v64, 4, v51
	v_mov_b64_e32 v[2:3], s[6:7]
	v_lshlrev_b32_e32 v82, 1, v6
	v_mov_b32_e32 v83, v129
	v_and_b32_e32 v84, -8, v8
	v_ashrrev_i32_e32 v65, 4, v10
	v_mad_i64_i32 v[4:5], s[6:7], v64, s88, v[2:3]
	s_waitcnt vmcnt(0)
	v_lshl_add_u64 v[32:33], s[0:1], 0, v[82:83]
	v_ashrrev_i32_e32 v85, 31, v84
	v_mad_i64_i32 v[2:3], s[6:7], v65, s88, v[2:3]
	v_lshl_add_u64 v[4:5], v[4:5], 0, v[128:129]
	v_lshl_add_u64 v[6:7], v[32:33], 0, s[90:91]
	v_lshlrev_b64 v[34:35], 1, v[84:85]
	v_lshl_add_u64 v[2:3], v[2:3], 0, v[128:129]
	v_lshl_add_u64 v[8:9], v[6:7], 0, v[34:35]
	global_load_dwordx4 v[16:19], v[4:5], off
	global_load_dwordx4 v[20:23], v[2:3], off
	global_load_dwordx4 v[24:27], v[8:9], off
	v_ashrrev_i32_e32 v2, 3, v10
	v_and_b32_e32 v86, -8, v2
	v_ashrrev_i32_e32 v87, 31, v86
	v_lshlrev_b64 v[36:37], 1, v[86:87]
	v_lshl_add_u64 v[2:3], v[6:7], 0, v[36:37]
	global_load_dwordx4 v[28:31], v[2:3], off
	v_and_b32_e32 v38, 48, v51
	v_mov_b32_e32 v39, v129
	v_lshl_add_u64 v[4:5], v[0:1], 0, v[38:39]
	v_add_co_u32_e32 v0, vcc, s61, v4
	s_mov_b64 s[6:7], 0x1000
	s_nop 0
	v_addc_co_u32_e32 v1, vcc, 0, v5, vcc
	global_load_dwordx4 v[0:3], v[0:1], off
	v_lshl_add_u64 v[12:13], v[4:5], 0, s[6:7]
	global_load_dwordx4 v[4:7], v[12:13], off offset:64
	global_load_dwordx4 v[8:11], v[12:13], off offset:128
	s_nop 0
	global_load_dwordx4 v[12:15], v[12:13], off offset:192
	v_mul_lo_u32 v93, v64, s89
	s_add_u32 s0, s0, 0xfff61400
	v_lshlrev_b32_e32 v95, 1, v48
	v_mul_lo_u32 v96, v65, s89
	v_mul_lo_u32 v97, v84, s30
	v_mul_lo_u32 v98, v86, s30
	v_add_u32_e32 v40, v93, v128
	s_addc_u32 s1, s1, -1
	v_or_b32_e32 v39, v97, v95
	v_add_u32_e32 v41, v96, v128
	s_barrier
	v_mul_u32_u24_e32 v94, 0x88, v92
	v_lshl_add_u32 v50, v94, 1, v38
	v_bfe_u32 v99, v51, 4, 2
	v_lshl_or_b32 v100, v99, 2, v80
	v_mov_b32_e32 v75, 0
	s_waitcnt vmcnt(7)
	ds_write_b128 v40, v[16:19]
	s_waitcnt vmcnt(6)
	ds_write_b128 v41, v[20:23]
	s_waitcnt vmcnt(5)
	ds_write_b16 v39, v24 offset:34816
	ds_write_b16_d16_hi v39, v24 offset:34960
	ds_write_b16 v39, v25 offset:35104
	ds_write_b16_d16_hi v39, v25 offset:35248
	ds_write_b16 v39, v26 offset:35392
	ds_write_b16_d16_hi v39, v26 offset:35536
	ds_write_b16 v39, v27 offset:35680
	ds_write_b16_d16_hi v39, v27 offset:35824
	v_or_b32_e32 v16, v98, v95
	v_mov_b64_e32 v[24:25], s[0:1]
	s_waitcnt vmcnt(4)
	ds_write_b16 v16, v28 offset:34816
	ds_write_b16_d16_hi v16, v28 offset:34960
	ds_write_b16 v16, v29 offset:35104
	ds_write_b16_d16_hi v16, v29 offset:35248
	ds_write_b16 v16, v30 offset:35392
	ds_write_b16_d16_hi v16, v30 offset:35536
	ds_write_b16 v16, v31 offset:35680
	ds_write_b16_d16_hi v16, v31 offset:35824
	v_mad_i64_i32 v[16:17], s[0:1], v64, s88, v[24:25]
	s_mov_b32 s0, 0xfff61800
	s_mov_b32 s1, -1
	v_lshl_add_u64 v[28:29], v[32:33], 0, s[0:1]
	v_mad_i64_i32 v[24:25], s[0:1], v65, s88, v[24:25]
	v_lshl_add_u64 v[16:17], v[16:17], 0, v[128:129]
	v_lshl_add_u64 v[20:21], v[28:29], 0, v[34:35]
	v_lshl_add_u64 v[24:25], v[24:25], 0, v[128:129]
	v_lshl_add_u64 v[28:29], v[28:29], 0, v[36:37]
	global_load_dwordx4 v[16:19], v[16:17], off
	s_nop 0
	global_load_dwordx4 v[20:23], v[20:21], off
	s_nop 0
	global_load_dwordx4 v[24:27], v[24:25], off
	s_nop 0
	global_load_dwordx4 v[28:31], v[28:29], off
	s_waitcnt lgkmcnt(0)
	s_barrier
; DEV void sb_item(const Params& p, int item, unsigned char* smem) {
;     ...
;     qk_tile(qf, sK, s, fr, fq);
; #pragma unroll
;     for (int mt = 0; mt < MT; ++mt)
; #pragma unroll
;       for (int j = 0; j < 4; ++j) {
;         const int tq = q0 + mt * 16 + fq * 4 + j;
;         float lk[4], lb[4], inc[4], tot[4];
; #pragma unroll
;         for (int jt = 0; jt < 4; ++jt) {
;           const int sk = kt * 64 + jt * 16 + fr;
;           const float z = s[mt][jt][j] * scale;
;           const float sp = fmaxf(z, 0.f) + __logf(1.0f + __expf(-fabsf(z)));
;           lk[jt] = (sk < tq) ? -sp : 0.f;
;           lb[jt] = z - sp;
;           float x = lk[jt];
;           x += dpp_f<0x101>(x); x += dpp_f<0x102>(x); x += dpp_f<0x104>(x); x += dpp_f<0x108>(x);
;           inc[jt] = x;
;           tot[jt] = grp16_sum_fast(lk[jt]);
;         }
	ds_read_b128 v[32:35], v50
	ds_read_b128 v[52:55], v50 offset:64
	s_waitcnt vmcnt(7) lgkmcnt(1)
	v_mfma_f32_16x16x32_bf16 v[32:35], v[0:3], v[32:35], 0
	ds_read_b128 v[36:39], v50 offset:4352
	ds_read_b128 v[40:43], v50 offset:8704
	ds_read_b128 v[44:47], v50 offset:13056
	s_waitcnt vmcnt(6) lgkmcnt(3)
	v_mfma_f32_16x16x32_bf16 v[32:35], v[4:7], v[52:55], v[32:35]
	ds_read_b128 v[52:55], v50 offset:4416
	ds_read_b128 v[66:69], v50 offset:8896
	s_waitcnt lgkmcnt(4)
	v_mfma_f32_16x16x32_bf16 v[36:39], v[0:3], v[36:39], 0
	s_waitcnt lgkmcnt(1)
	v_mfma_f32_16x16x32_bf16 v[36:39], v[4:7], v[52:55], v[36:39]
	ds_read_b128 v[52:55], v50 offset:8768
	v_mfma_f32_16x16x32_bf16 v[40:43], v[0:3], v[40:43], 0
	s_waitcnt lgkmcnt(0)
	v_mfma_f32_16x16x32_bf16 v[40:43], v[4:7], v[52:55], v[40:43]
	ds_read_b128 v[52:55], v50 offset:13120
	v_mfma_f32_16x16x32_bf16 v[44:47], v[0:3], v[44:47], 0
	s_waitcnt lgkmcnt(0)
	v_mfma_f32_16x16x32_bf16 v[44:47], v[4:7], v[52:55], v[44:47]
	ds_read_b128 v[52:55], v50 offset:128
	s_waitcnt vmcnt(5) lgkmcnt(0)
	v_mfma_f32_16x16x32_bf16 v[32:35], v[8:11], v[52:55], v[32:35]
	ds_read_b128 v[52:55], v50 offset:4480
	s_waitcnt lgkmcnt(0)
	v_mfma_f32_16x16x32_bf16 v[36:39], v[8:11], v[52:55], v[36:39]
	ds_read_b128 v[52:55], v50 offset:8832
	s_waitcnt lgkmcnt(0)
	v_mfma_f32_16x16x32_bf16 v[56:59], v[8:11], v[52:55], v[40:43]
	s_nop 2
	ds_read_b128 v[40:43], v50 offset:13184
	s_waitcnt lgkmcnt(0)
	v_mfma_f32_16x16x32_bf16 v[60:63], v[8:11], v[40:43], v[44:47]
	ds_read_b128 v[40:43], v50 offset:192
	s_waitcnt vmcnt(4) lgkmcnt(0)
	v_mfma_f32_16x16x32_bf16 v[44:47], v[12:15], v[40:43], v[32:35]
	s_nop 2
	ds_read_b128 v[32:35], v50 offset:4544
	s_waitcnt lgkmcnt(0)
	v_mfma_f32_16x16x32_bf16 v[40:43], v[12:15], v[32:35], v[36:39]
	s_nop 1
	v_mul_f32_e32 v54, 0x3db504f3, v44
	v_mul_f32_e64 v32, |v54|, s31
	v_exp_f32_e32 v44, v32
	v_max_f32_e32 v52, 0, v54
	v_mfma_f32_16x16x32_bf16 v[36:39], v[12:15], v[66:69], v[56:59]
	ds_read_b128 v[32:35], v50 offset:13248
	v_add_f32_e32 v44, 1.0, v44
	s_nop 0
	v_mul_f32_e32 v59, 0x3db504f3, v40
	v_mul_f32_e64 v40, |v59|, s31
	s_nop 0
	s_nop 0
	v_log_f32_e32 v44, v44
	v_lshl_or_b32 v51, s4, 6, v92
	s_waitcnt lgkmcnt(0)
	v_mfma_f32_16x16x32_bf16 v[32:35], v[12:15], v[32:35], v[60:63]
	v_max_f32_e32 v55, 0, v59
	v_mul_f32_e32 v53, 0x3f317217, v44
	v_fma_f32 v53, v44, s29, -v53
	v_fmac_f32_e32 v53, 0x3377d1cf, v44
	v_fmac_f32_e32 v53, 0x3f317217, v44
	s_nop 0
	v_mul_f32_e32 v63, 0x3db504f3, v36
	v_mul_f32_e64 v36, |v63|, s31
	v_mov_b32_e32 v44, v53
	s_nop 0
	v_mov_b32_e32 v44, v44
	v_add_f32_e32 v56, v52, v44
	v_cmp_lt_i32_e32 vcc, v51, v100
	v_exp_f32_e32 v36, v36
	s_nop 0
	v_cndmask_b32_e64 v44, 0, -v56, vcc
	v_add_f32_e32 v36, 1.0, v36
	s_nop 0
	v_add_f32_dpp v52, v44, v44 row_shl:1 row_mask:0xf bank_mask:0xf bound_ctrl:1
	s_nop 1
	v_add_f32_dpp v52, v52, v52 row_shl:2 row_mask:0xf bank_mask:0xf bound_ctrl:1
	s_nop 1
	v_add_f32_dpp v57, v52, v52 row_shl:4 row_mask:0xf bank_mask:0xf bound_ctrl:1
	v_exp_f32_e32 v52, v40
	v_add_f32_dpp v40, v44, v44 row_ror:8 row_mask:0xf bank_mask:0xf bound_ctrl:1
	v_mov_b32_dpp v58, v57 row_shl:8 row_mask:0xf bank_mask:0xf bound_ctrl:1
	v_add_f32_e32 v44, 1.0, v52
	s_nop 0
	v_add_f32_dpp v40, v40, v40 row_ror:4 row_mask:0xf bank_mask:0xf bound_ctrl:1
	s_nop 0
	s_nop 0
	s_nop 0
	v_log_f32_e32 v53, v44
	v_or_b32_e32 v52, 16, v51
	v_add_f32_dpp v40, v40, v40 row_ror:2 row_mask:0xf bank_mask:0xf bound_ctrl:1
	v_mul_f32_e32 v60, 0x3f317217, v53
	v_fma_f32 v60, v53, s29, -v60
	v_fmac_f32_e32 v60, 0x3377d1cf, v53
	v_fmac_f32_e32 v60, 0x3f317217, v53
	s_nop 0
	v_mov_b32_dpp v44, v40 row_ror:1 row_mask:0xf bank_mask:0xf bound_ctrl:1
	s_nop 0
	v_mov_b32_e32 v53, v60
	s_nop 0
	v_mov_b32_e32 v53, v53
	v_add_f32_e32 v60, v55, v53
	v_cmp_lt_i32_e64 s[0:1], v52, v100
	v_cmp_gt_f32_e64 s[4:5], s84, v36
	s_nop 0
	v_cndmask_b32_e64 v53, 0, -v60, s[0:1]
	s_nop 1
	v_add_f32_dpp v55, v53, v53 row_shl:1 row_mask:0xf bank_mask:0xf bound_ctrl:1
	v_add_f32_dpp v53, v53, v53 row_ror:8 row_mask:0xf bank_mask:0xf bound_ctrl:1
	s_nop 0
	v_add_f32_dpp v55, v55, v55 row_shl:2 row_mask:0xf bank_mask:0xf bound_ctrl:1
	v_add_f32_dpp v53, v53, v53 row_ror:4 row_mask:0xf bank_mask:0xf bound_ctrl:1
	s_nop 0
	v_add_f32_dpp v61, v55, v55 row_shl:4 row_mask:0xf bank_mask:0xf bound_ctrl:1
	v_add_f32_dpp v66, v53, v53 row_ror:2 row_mask:0xf bank_mask:0xf bound_ctrl:1
	v_cndmask_b32_e64 v53, 0, 32, s[4:5]
	v_ldexp_f32 v36, v36, v53
	v_log_f32_e32 v53, v36
	v_or_b32_e32 v36, 32, v51
	v_max_f32_e32 v55, 0, v63
	v_mov_b32_dpp v62, v61 row_shl:8 row_mask:0xf bank_mask:0xf bound_ctrl:1
	v_mul_f32_e32 v68, 0x3f317217, v53
	v_fma_f32 v68, v53, s29, -v68
	v_fmac_f32_e32 v68, 0x3377d1cf, v53
	v_fmac_f32_e32 v68, 0x3f317217, v53
	v_cmp_lt_f32_e64 s[6:7], |v53|, s36
	v_mov_b32_dpp v67, v66 row_ror:1 row_mask:0xf bank_mask:0xf bound_ctrl:1
	s_nop 0
	v_cndmask_b32_e64 v53, v53, v68, s[6:7]
	v_cndmask_b32_e64 v68, 0, v171, s[4:5]
	v_sub_f32_e32 v53, v53, v68
	v_add_f32_e32 v68, v55, v53
	v_cmp_lt_i32_e64 s[4:5], v36, v100
	s_nop 1
	v_cndmask_b32_e64 v55, 0, -v68, s[4:5]
	s_nop 1
	v_add_f32_dpp v53, v55, v55 row_shl:1 row_mask:0xf bank_mask:0xf bound_ctrl:1
	v_add_f32_dpp v55, v55, v55 row_ror:8 row_mask:0xf bank_mask:0xf bound_ctrl:1
	s_nop 0
	v_add_f32_dpp v53, v53, v53 row_shl:2 row_mask:0xf bank_mask:0xf bound_ctrl:1
	v_add_f32_dpp v55, v55, v55 row_ror:4 row_mask:0xf bank_mask:0xf bound_ctrl:1
	s_nop 0
	v_add_f32_dpp v69, v53, v53 row_shl:4 row_mask:0xf bank_mask:0xf bound_ctrl:1
	v_mul_f32_e32 v53, 0x3db504f3, v32
	v_mul_f32_e64 v32, |v53|, s31
	v_exp_f32_e32 v32, v32
	v_add_f32_dpp v71, v55, v55 row_ror:2 row_mask:0xf bank_mask:0xf bound_ctrl:1
	v_max_f32_e32 v73, 0, v53
	v_mov_b32_dpp v70, v69 row_shl:8 row_mask:0xf bank_mask:0xf bound_ctrl:1
	v_add_f32_e32 v32, 1.0, v32
	s_nop 0
	v_mov_b32_dpp v72, v71 row_ror:1 row_mask:0xf bank_mask:0xf bound_ctrl:1
	s_nop 0
	s_nop 0
	s_nop 0
	v_log_f32_e32 v55, v32
	v_or_b32_e32 v32, 48, v51
	v_mul_f32_e32 v74, 0x3f317217, v55
	v_fma_f32 v74, v55, s29, -v74
	v_fmac_f32_e32 v74, 0x3377d1cf, v55
	v_fmac_f32_e32 v74, 0x3f317217, v55
	s_nop 0
	s_nop 1
	v_mov_b32_e32 v55, v74
	s_nop 0
	v_mov_b32_e32 v55, v55
	v_add_f32_e32 v76, v73, v55
	v_cmp_lt_i32_e64 s[6:7], v32, v100
	s_nop 1
	v_cndmask_b32_e64 v55, 0, -v76, s[6:7]
	s_nop 1
	v_add_f32_dpp v73, v55, v55 row_shl:1 row_mask:0xf bank_mask:0xf bound_ctrl:1
	v_add_f32_dpp v55, v55, v55 row_ror:8 row_mask:0xf bank_mask:0xf bound_ctrl:1
	s_nop 0
	v_add_f32_dpp v73, v73, v73 row_shl:2 row_mask:0xf bank_mask:0xf bound_ctrl:1
	v_add_f32_dpp v55, v55, v55 row_ror:4 row_mask:0xf bank_mask:0xf bound_ctrl:1
	s_nop 0
	v_add_f32_dpp v77, v73, v73 row_shl:4 row_mask:0xf bank_mask:0xf bound_ctrl:1
	v_add_f32_dpp v73, v55, v55 row_ror:2 row_mask:0xf bank_mask:0xf bound_ctrl:1
	v_mov_b32_e32 v55, 0
	v_mov_b32_dpp v78, v77 row_shl:8 row_mask:0xf bank_mask:0xf bound_ctrl:1
	v_mov_b32_dpp v74, v73 row_ror:1 row_mask:0xf bank_mask:0xf bound_ctrl:1
	s_and_saveexec_b64 s[10:11], s[6:7]
	s_cbranch_execz .LBB0_424
; DEV void sb_item(const Params& p, int item, unsigned char* smem) {
;     ...
;     for (int mt = 0; mt < MT; ++mt)
; #pragma unroll
;       for (int j = 0; j < 4; ++j) {
;         const int tq = q0 + mt * 16 + fq * 4 + j;
;         float lk[4], lb[4], inc[4], tot[4];
; #pragma unroll
;         for (int jt = 0; jt < 4; ++jt) {
;           const int sk = kt * 64 + jt * 16 + fr;
;           const float z = s[mt][jt][j] * scale;
;           const float sp = fmaxf(z, 0.f) + __logf(1.0f + __expf(-fabsf(z)));
;           lk[jt] = (sk < tq) ? -sp : 0.f;
;           lb[jt] = z - sp;
;           float x = lk[jt];
;           x += dpp_f<0x101>(x); x += dpp_f<0x102>(x); x += dpp_f<0x104>(x); x += dpp_f<0x108>(x);
;           inc[jt] = x;
;           tot[jt] = grp16_sum_fast(lk[jt]);
;         }
;         float after = 0.f;
; #pragma unroll
;     ...
;           const int sk = kt * 64 + jt * 16 + fr;
;           const float e = lb[jt] + (inc[jt] - lk[jt]) + after + run[mt][j];
;           const float a = (sk < tq) ? __expf(e) : 0.f;
;           sP[(mt * 16 + fq * 4 + j) * VS + jt * 16 + fr] = f2bf(a);
;           after += tot[jt];
;         }
;         run[mt][j] += after;
	v_add_f32_e32 v75, v77, v78
	v_sub_f32_e32 v53, v53, v76
	v_add_f32_e32 v75, v76, v75
	v_add_f32_e32 v53, v53, v75
	v_add_f32_e32 v53, 0, v53
	v_mul_f32_e32 v53, 0x3fb8aa3b, v53
	v_exp_f32_e32 v53, v53
	s_nop 0
	v_cvt_pk_bf16_f32 v75, v53, s0
.LBB0_424:
	s_or_b64 exec, exec, s[10:11]
	v_add_f32_e32 v57, v57, v58
	v_add_f32_e32 v58, v61, v62
	v_add_f32_e32 v62, v69, v70
	v_sub_f32_e32 v78, v54, v56
	v_sub_f32_e32 v54, v59, v60
	v_add_f32_e32 v59, v66, v67
	v_sub_f32_e32 v61, v63, v68
	v_add_f32_e32 v66, v73, v74
	v_add_f32_e32 v62, v68, v62
	v_add_f32_e32 v66, 0, v66
	v_add_f32_e32 v61, v61, v62
	v_add_f32_e32 v63, v71, v72
	v_add_f32_e32 v61, v61, v66
	v_add_f32_e32 v58, v60, v58
	v_mul_f32_e32 v61, 0x3fb8aa3b, v61
	v_add_f32_e32 v62, v63, v66
	v_add_f32_e32 v54, v54, v58
	v_exp_f32_e32 v61, v61
	v_add_f32_e32 v54, v54, v62
	s_movk_i32 s6, 0x900
	v_mul_f32_e32 v54, 0x3fb8aa3b, v54
	v_mul_lo_u32 v53, v49, s6
	v_exp_f32_e32 v54, v54
	v_add_u32_e32 v53, 0x11800, v53
	v_mul_u32_u24_e32 v76, 0x240, v99
	v_lshl_or_b32 v77, v92, 1, v53
	v_cvt_pk_bf16_f32 v58, v61, s0
	v_add_u32_e32 v101, v77, v76
	v_cndmask_b32_e64 v58, 0, v58, s[4:5]
	v_add_f32_e32 v56, v56, v57
	ds_write_b16 v101, v58 offset:64
	v_cvt_pk_bf16_f32 v58, v54, s0
	v_add_f32_e32 v54, v59, v62
	v_add_f32_e32 v56, v78, v56
	v_mul_f32_e32 v57, 0x3db504f3, v45
	v_add_f32_e32 v56, v56, v54
	v_mul_f32_e64 v45, |v57|, s31
	v_mul_f32_e32 v56, 0x3fb8aa3b, v56
	v_exp_f32_e32 v45, v45
	v_exp_f32_e32 v56, v56
	v_cndmask_b32_e64 v58, 0, v58, s[0:1]
	ds_write_b16 v101, v58 offset:32
	v_add_f32_e32 v45, 1.0, v45
	v_cvt_pk_bf16_f32 v56, v56, s0
	v_cmp_gt_f32_e64 s[0:1], s84, v45
	v_mul_f32_e32 v59, 0x3db504f3, v41
	v_mul_f32_e64 v41, |v59|, s31
	v_cndmask_b32_e64 v58, 0, 32, s[0:1]
	v_ldexp_f32 v45, v45, v58
	v_log_f32_e32 v45, v45
	v_exp_f32_e32 v41, v41
	v_cndmask_b32_e32 v56, 0, v56, vcc
	v_mul_f32_e32 v37, 0x3db504f3, v37
	v_mul_f32_e32 v58, 0x3f317217, v45
	v_fma_f32 v58, v45, s29, -v58
	v_fmac_f32_e32 v58, 0x3377d1cf, v45
	v_fmac_f32_e32 v58, 0x3f317217, v45
	v_cmp_lt_f32_e64 vcc, |v45|, s36
	v_add_f32_e32 v41, 1.0, v41
	v_mul_f32_e32 v72, 0x3db504f3, v33
	v_cndmask_b32_e32 v45, v45, v58, vcc
	v_cndmask_b32_e64 v58, 0, v171, s[0:1]
	s_nop 0
	v_mul_f32_e64 v33, |v72|, s31
	v_exp_f32_e32 v71, v33
	s_nop 0
	s_nop 0
	v_log_f32_e32 v61, v41
	v_add_f32_e32 v71, 1.0, v71
	ds_write_b16 v101, v75 offset:96
	ds_write_b16 v101, v56
	v_mul_f32_e32 v63, 0x3f317217, v61
	v_fma_f32 v63, v61, s29, -v63
	v_fmac_f32_e32 v63, 0x3377d1cf, v61
	v_fmac_f32_e32 v63, 0x3f317217, v61
	s_nop 0
	v_max_f32_e32 v56, 0, v57
	v_sub_f32_e32 v45, v45, v58
	v_mov_b32_e32 v61, v63
	s_nop 0
	v_mov_b32_e32 v61, v61
	v_mul_f32_e64 v63, |v37|, s31
	v_exp_f32_e32 v67, v63
	v_max_f32_e32 v62, 0, v59
	v_max_f32_e32 v69, 0, v37
	v_max_f32_e32 v74, 0, v72
	v_add_f32_e32 v67, 1.0, v67
	s_nop 0
	v_add_f32_e32 v56, v56, v45
	v_cmp_gt_i32_e32 vcc, v51, v100
	s_nop 0
	s_nop 0
	v_log_f32_e32 v68, v67
	v_add_f32_e32 v61, v62, v61
	v_cmp_gt_i32_e64 s[0:1], v52, v100
	v_cndmask_b32_e64 v45, -v56, 0, vcc
	v_mul_f32_e32 v70, 0x3f317217, v68
	v_fma_f32 v70, v68, s29, -v70
	v_fmac_f32_e32 v70, 0x3377d1cf, v68
	v_fmac_f32_e32 v70, 0x3f317217, v68
	s_nop 0
	v_cndmask_b32_e64 v66, -v61, 0, s[0:1]
	v_add_f32_dpp v58, v45, v45 row_shl:1 row_mask:0xf bank_mask:0xf bound_ctrl:1
	v_mov_b32_e32 v68, v70
	v_cmp_gt_f32_e64 s[6:7], s84, v71
	s_nop 0
	v_mov_b32_e32 v68, v68
	v_cndmask_b32_e64 v73, 0, 32, s[6:7]
	v_ldexp_f32 v71, v71, v73
	v_log_f32_e32 v73, v71
	v_add_f32_e32 v68, v69, v68
	v_cmp_gt_i32_e64 s[4:5], v36, v100
	v_add_f32_dpp v45, v45, v45 row_ror:8 row_mask:0xf bank_mask:0xf bound_ctrl:1
	v_mul_f32_e32 v75, 0x3f317217, v73
	v_fma_f32 v75, v73, s29, -v75
	v_fmac_f32_e32 v75, 0x3377d1cf, v73
	v_fmac_f32_e32 v75, 0x3f317217, v73
	v_cmp_lt_f32_e64 s[10:11], |v73|, s36
	v_cndmask_b32_e64 v70, -v68, 0, s[4:5]
	v_add_f32_dpp v62, v66, v66 row_shl:1 row_mask:0xf bank_mask:0xf bound_ctrl:1
	v_cndmask_b32_e64 v73, v73, v75, s[10:11]
	v_cndmask_b32_e64 v75, 0, v171, s[6:7]
	v_sub_f32_e32 v73, v73, v75
	v_add_f32_e32 v75, v74, v73
	v_cmp_le_i32_e64 s[6:7], v32, v100
	v_add_f32_dpp v66, v66, v66 row_ror:8 row_mask:0xf bank_mask:0xf bound_ctrl:1
	v_add_f32_dpp v69, v70, v70 row_shl:1 row_mask:0xf bank_mask:0xf bound_ctrl:1
	v_cndmask_b32_e64 v73, 0, -v75, s[6:7]
	v_add_f32_dpp v70, v70, v70 row_ror:8 row_mask:0xf bank_mask:0xf bound_ctrl:1
	v_add_f32_dpp v58, v58, v58 row_shl:2 row_mask:0xf bank_mask:0xf bound_ctrl:1
	v_add_f32_dpp v74, v73, v73 row_shl:1 row_mask:0xf bank_mask:0xf bound_ctrl:1
	v_add_f32_dpp v73, v73, v73 row_ror:8 row_mask:0xf bank_mask:0xf bound_ctrl:1
	v_add_f32_dpp v45, v45, v45 row_ror:4 row_mask:0xf bank_mask:0xf bound_ctrl:1
	v_add_f32_dpp v62, v62, v62 row_shl:2 row_mask:0xf bank_mask:0xf bound_ctrl:1
	v_add_f32_dpp v66, v66, v66 row_ror:4 row_mask:0xf bank_mask:0xf bound_ctrl:1
	v_add_f32_dpp v69, v69, v69 row_shl:2 row_mask:0xf bank_mask:0xf bound_ctrl:1
	v_add_f32_dpp v70, v70, v70 row_ror:4 row_mask:0xf bank_mask:0xf bound_ctrl:1
	v_add_f32_dpp v74, v74, v74 row_shl:2 row_mask:0xf bank_mask:0xf bound_ctrl:1
	v_add_f32_dpp v73, v73, v73 row_ror:4 row_mask:0xf bank_mask:0xf bound_ctrl:1
	v_add_f32_dpp v58, v58, v58 row_shl:4 row_mask:0xf bank_mask:0xf bound_ctrl:1
	v_add_f32_dpp v41, v45, v45 row_ror:2 row_mask:0xf bank_mask:0xf bound_ctrl:1
	v_add_f32_dpp v62, v62, v62 row_shl:4 row_mask:0xf bank_mask:0xf bound_ctrl:1
	v_add_f32_dpp v66, v66, v66 row_ror:2 row_mask:0xf bank_mask:0xf bound_ctrl:1
	v_add_f32_dpp v69, v69, v69 row_shl:4 row_mask:0xf bank_mask:0xf bound_ctrl:1
	v_add_f32_dpp v70, v70, v70 row_ror:2 row_mask:0xf bank_mask:0xf bound_ctrl:1
	v_add_f32_dpp v76, v74, v74 row_shl:4 row_mask:0xf bank_mask:0xf bound_ctrl:1
	v_add_f32_dpp v73, v73, v73 row_ror:2 row_mask:0xf bank_mask:0xf bound_ctrl:1
	v_mov_b32_dpp v60, v58 row_shl:8 row_mask:0xf bank_mask:0xf bound_ctrl:1
	v_mov_b32_dpp v45, v41 row_ror:1 row_mask:0xf bank_mask:0xf bound_ctrl:1
	v_mov_b32_dpp v63, v62 row_shl:8 row_mask:0xf bank_mask:0xf bound_ctrl:1
	v_mov_b32_dpp v67, v66 row_ror:1 row_mask:0xf bank_mask:0xf bound_ctrl:1
	v_mov_b32_dpp v33, v69 row_shl:8 row_mask:0xf bank_mask:0xf bound_ctrl:1
	v_mov_b32_dpp v71, v70 row_ror:1 row_mask:0xf bank_mask:0xf bound_ctrl:1
	v_mov_b32_dpp v77, v76 row_shl:8 row_mask:0xf bank_mask:0xf bound_ctrl:1
	v_mov_b32_dpp v74, v73 row_ror:1 row_mask:0xf bank_mask:0xf bound_ctrl:1
	s_and_saveexec_b64 s[10:11], s[6:7]
	s_cbranch_execz .LBB0_426
	v_add_f32_e32 v55, v76, v77
	v_sub_f32_e32 v72, v72, v75
	v_add_f32_e32 v55, v75, v55
	v_add_f32_e32 v55, v72, v55
	v_add_f32_e32 v55, 0, v55
	v_mul_f32_e32 v55, 0x3fb8aa3b, v55
	v_exp_f32_e32 v55, v55
	s_nop 0
	v_cvt_pk_bf16_f32 v55, v55, s0
; DEV void sb_item(const Params& p, int item, unsigned char* smem) {
;     ...
;     for (int mt = 0; mt < MT; ++mt)
; #pragma unroll
;       for (int j = 0; j < 4; ++j) {
;         const int tq = q0 + mt * 16 + fq * 4 + j;
;         float lk[4], lb[4], inc[4], tot[4];
; #pragma unroll
;         for (int jt = 0; jt < 4; ++jt) {
;           const int sk = kt * 64 + jt * 16 + fr;
;           const float z = s[mt][jt][j] * scale;
;           const float sp = fmaxf(z, 0.f) + __logf(1.0f + __expf(-fabsf(z)));
;           lk[jt] = (sk < tq) ? -sp : 0.f;
;           lb[jt] = z - sp;
;           float x = lk[jt];
;           x += dpp_f<0x101>(x); x += dpp_f<0x102>(x); x += dpp_f<0x104>(x); x += dpp_f<0x108>(x);
;           inc[jt] = x;
;           tot[jt] = grp16_sum_fast(lk[jt]);
;         }
;         float after = 0.f;
; #pragma unroll
;     ...
;           const int sk = kt * 64 + jt * 16 + fr;
;           const float e = lb[jt] + (inc[jt] - lk[jt]) + after + run[mt][j];
;           const float a = (sk < tq) ? __expf(e) : 0.f;
;           sP[(mt * 16 + fq * 4 + j) * VS + jt * 16 + fr] = f2bf(a);
;           after += tot[jt];
;         }
;         run[mt][j] += after;
.LBB0_426:
	s_or_b64 exec, exec, s[10:11]
	v_add_f32_e32 v33, v69, v33
	v_add_f32_e32 v58, v58, v60
	v_add_f32_e32 v60, v62, v63
	v_add_f32_e32 v62, v66, v67
	v_sub_f32_e32 v37, v37, v68
	v_add_f32_e32 v66, v73, v74
	v_add_f32_e32 v33, v68, v33
	ds_write_b16 v101, v55 offset:240
	v_add_f32_e32 v55, 0, v66
	v_add_f32_e32 v33, v37, v33
	v_add_f32_e32 v33, v33, v55
	v_mul_f32_e32 v33, 0x3fb8aa3b, v33
	v_exp_f32_e32 v33, v33
	v_add_f32_e32 v63, v70, v71
	v_sub_f32_e32 v59, v59, v61
	v_add_f32_e32 v37, v63, v55
	v_add_f32_e32 v55, v61, v60
	v_add_f32_e32 v55, v59, v55
	v_cvt_pk_bf16_f32 v33, v33, s0
	v_add_f32_e32 v55, v55, v37
	v_cndmask_b32_e64 v33, v33, 0, s[4:5]
	v_sub_f32_e32 v57, v57, v56
	v_mul_f32_e32 v55, 0x3fb8aa3b, v55
	ds_write_b16 v101, v33 offset:208
	v_add_f32_e32 v33, v62, v37
	v_add_f32_e32 v37, v56, v58
	v_exp_f32_e32 v55, v55
	v_add_f32_e32 v37, v57, v37
	v_mul_f32_e32 v46, 0x3db504f3, v46
	v_add_f32_e32 v37, v37, v33
	v_mul_f32_e64 v56, |v46|, s31
	v_mul_f32_e32 v37, 0x3fb8aa3b, v37
	v_exp_f32_e32 v56, v56
	v_exp_f32_e32 v37, v37
	v_cvt_pk_bf16_f32 v55, v55, s0
	v_cndmask_b32_e64 v55, v55, 0, s[0:1]
	ds_write_b16 v101, v55 offset:176
	v_add_f32_e32 v55, 1.0, v56
	v_cvt_pk_bf16_f32 v37, v37, s0
	v_cmp_gt_f32_e64 s[0:1], s84, v55
	v_mul_f32_e32 v57, 0x3db504f3, v42
	v_mul_f32_e64 v42, |v57|, s31
	v_cndmask_b32_e64 v56, 0, 32, s[0:1]
	v_ldexp_f32 v55, v55, v56
	v_log_f32_e32 v55, v55
	v_exp_f32_e32 v42, v42
	v_cndmask_b32_e64 v37, v37, 0, vcc
	v_mul_f32_e32 v38, 0x3db504f3, v38
	v_mul_f32_e32 v56, 0x3f317217, v55
	v_fma_f32 v56, v55, s29, -v56
	v_fmac_f32_e32 v56, 0x3377d1cf, v55
	v_fmac_f32_e32 v56, 0x3f317217, v55
	v_cmp_lt_f32_e64 vcc, |v55|, s36
	v_add_f32_e32 v42, 1.0, v42
	v_mul_f32_e32 v71, 0x3db504f3, v34
	v_cndmask_b32_e32 v55, v55, v56, vcc
	v_cndmask_b32_e64 v56, 0, v171, s[0:1]
	s_nop 0
	v_mul_f32_e64 v34, |v71|, s31
	v_exp_f32_e32 v34, v34
	s_nop 0
	s_nop 0
	v_log_f32_e32 v59, v42
	v_add_f32_e32 v34, 1.0, v34
	v_or_b32_e32 v102, 2, v100
	ds_write_b16 v101, v37 offset:144
	v_mul_f32_e32 v61, 0x3f317217, v59
	v_fma_f32 v61, v59, s29, -v61
	v_fmac_f32_e32 v61, 0x3377d1cf, v59
	v_fmac_f32_e32 v61, 0x3f317217, v59
	s_nop 0
	v_max_f32_e32 v37, 0, v46
	v_sub_f32_e32 v55, v55, v56
	v_mov_b32_e32 v59, v61
	s_nop 0
	v_mov_b32_e32 v59, v59
	v_mul_f32_e64 v61, |v38|, s31
	v_exp_f32_e32 v63, v61
	v_max_f32_e32 v60, 0, v57
	v_max_f32_e32 v67, 0, v38
	v_max_f32_e32 v72, 0, v71
	v_add_f32_e32 v63, 1.0, v63
	s_nop 0
	v_add_f32_e32 v55, v37, v55
	v_cmp_lt_i32_e32 vcc, v51, v102
	s_nop 0
	s_nop 0
	v_log_f32_e32 v66, v63
	v_add_f32_e32 v59, v60, v59
	v_cmp_lt_i32_e64 s[0:1], v52, v102
	v_cndmask_b32_e64 v37, 0, -v55, vcc
	v_mul_f32_e32 v68, 0x3f317217, v66
	v_fma_f32 v68, v66, s29, -v68
	v_fmac_f32_e32 v68, 0x3377d1cf, v66
	v_fmac_f32_e32 v68, 0x3f317217, v66
	s_nop 0
	v_cndmask_b32_e64 v62, 0, -v59, s[0:1]
	v_add_f32_dpp v56, v37, v37 row_shl:1 row_mask:0xf bank_mask:0xf bound_ctrl:1
	v_mov_b32_e32 v66, v68
	v_cmp_gt_f32_e64 s[6:7], s84, v34
	s_nop 0
	v_mov_b32_e32 v66, v66
	v_cndmask_b32_e64 v70, 0, 32, s[6:7]
	v_ldexp_f32 v34, v34, v70
	v_log_f32_e32 v34, v34
	v_add_f32_e32 v66, v67, v66
	v_cmp_lt_i32_e64 s[4:5], v36, v102
	v_add_f32_dpp v37, v37, v37 row_ror:8 row_mask:0xf bank_mask:0xf bound_ctrl:1
	v_mul_f32_e32 v73, 0x3f317217, v34
	v_fma_f32 v73, v34, s29, -v73
	v_fmac_f32_e32 v73, 0x3377d1cf, v34
	v_fmac_f32_e32 v73, 0x3f317217, v34
	v_cmp_lt_f32_e64 s[10:11], |v34|, s36
	v_cndmask_b32_e64 v69, 0, -v66, s[4:5]
	v_add_f32_dpp v60, v62, v62 row_shl:1 row_mask:0xf bank_mask:0xf bound_ctrl:1
	v_cndmask_b32_e64 v34, v34, v73, s[10:11]
	v_cndmask_b32_e64 v73, 0, v171, s[6:7]
	v_sub_f32_e32 v34, v34, v73
	v_add_f32_e32 v74, v72, v34
	v_cmp_lt_i32_e64 s[6:7], v32, v102
	v_add_f32_dpp v62, v62, v62 row_ror:8 row_mask:0xf bank_mask:0xf bound_ctrl:1
	v_add_f32_dpp v67, v69, v69 row_shl:1 row_mask:0xf bank_mask:0xf bound_ctrl:1
	v_cndmask_b32_e64 v34, 0, -v74, s[6:7]
	v_add_f32_dpp v69, v69, v69 row_ror:8 row_mask:0xf bank_mask:0xf bound_ctrl:1
	v_add_f32_dpp v56, v56, v56 row_shl:2 row_mask:0xf bank_mask:0xf bound_ctrl:1
	v_add_f32_dpp v72, v34, v34 row_shl:1 row_mask:0xf bank_mask:0xf bound_ctrl:1
	v_add_f32_dpp v34, v34, v34 row_ror:8 row_mask:0xf bank_mask:0xf bound_ctrl:1
	v_add_f32_dpp v37, v37, v37 row_ror:4 row_mask:0xf bank_mask:0xf bound_ctrl:1
	v_add_f32_dpp v60, v60, v60 row_shl:2 row_mask:0xf bank_mask:0xf bound_ctrl:1
	v_add_f32_dpp v62, v62, v62 row_ror:4 row_mask:0xf bank_mask:0xf bound_ctrl:1
	v_add_f32_dpp v67, v67, v67 row_shl:2 row_mask:0xf bank_mask:0xf bound_ctrl:1
	v_add_f32_dpp v69, v69, v69 row_ror:4 row_mask:0xf bank_mask:0xf bound_ctrl:1
	v_add_f32_dpp v72, v72, v72 row_shl:2 row_mask:0xf bank_mask:0xf bound_ctrl:1
	v_add_f32_dpp v34, v34, v34 row_ror:4 row_mask:0xf bank_mask:0xf bound_ctrl:1
	v_add_f32_dpp v56, v56, v56 row_shl:4 row_mask:0xf bank_mask:0xf bound_ctrl:1
	v_add_f32_dpp v37, v37, v37 row_ror:2 row_mask:0xf bank_mask:0xf bound_ctrl:1
	v_add_f32_dpp v60, v60, v60 row_shl:4 row_mask:0xf bank_mask:0xf bound_ctrl:1
	v_add_f32_dpp v62, v62, v62 row_ror:2 row_mask:0xf bank_mask:0xf bound_ctrl:1
	v_add_f32_dpp v67, v67, v67 row_shl:4 row_mask:0xf bank_mask:0xf bound_ctrl:1
	v_add_f32_dpp v69, v69, v69 row_ror:2 row_mask:0xf bank_mask:0xf bound_ctrl:1
	v_add_f32_dpp v76, v72, v72 row_shl:4 row_mask:0xf bank_mask:0xf bound_ctrl:1
	v_add_f32_dpp v72, v34, v34 row_ror:2 row_mask:0xf bank_mask:0xf bound_ctrl:1
	v_mov_b32_dpp v58, v56 row_shl:8 row_mask:0xf bank_mask:0xf bound_ctrl:1
	v_mov_b32_dpp v42, v37 row_ror:1 row_mask:0xf bank_mask:0xf bound_ctrl:1
	v_mov_b32_dpp v61, v60 row_shl:8 row_mask:0xf bank_mask:0xf bound_ctrl:1
	v_mov_b32_dpp v63, v62 row_ror:1 row_mask:0xf bank_mask:0xf bound_ctrl:1
	v_mov_b32_dpp v68, v67 row_shl:8 row_mask:0xf bank_mask:0xf bound_ctrl:1
	v_mov_b32_dpp v70, v69 row_ror:1 row_mask:0xf bank_mask:0xf bound_ctrl:1
	v_mov_b32_dpp v77, v76 row_shl:8 row_mask:0xf bank_mask:0xf bound_ctrl:1
	v_mov_b32_dpp v73, v72 row_ror:1 row_mask:0xf bank_mask:0xf bound_ctrl:1
	v_mov_b32_e32 v34, 0
	v_mov_b32_e32 v75, 0
	s_and_saveexec_b64 s[10:11], s[6:7]
	s_cbranch_execz .LBB0_428
	v_add_f32_e32 v75, v76, v77
	v_sub_f32_e32 v71, v71, v74
	v_add_f32_e32 v74, v74, v75
	v_add_f32_e32 v71, v71, v74
	v_add_f32_e32 v71, 0, v71
	v_mul_f32_e32 v71, 0x3fb8aa3b, v71
	v_exp_f32_e32 v71, v71
	s_nop 0
	v_cvt_pk_bf16_f32 v75, v71, s0
; DEV void sb_item(const Params& p, int item, unsigned char* smem) {
;     ...
;     for (int mt = 0; mt < MT; ++mt)
; #pragma unroll
;       for (int j = 0; j < 4; ++j) {
;         const int tq = q0 + mt * 16 + fq * 4 + j;
;         float lk[4], lb[4], inc[4], tot[4];
; #pragma unroll
;         for (int jt = 0; jt < 4; ++jt) {
;           const int sk = kt * 64 + jt * 16 + fr;
;           const float z = s[mt][jt][j] * scale;
;           const float sp = fmaxf(z, 0.f) + __logf(1.0f + __expf(-fabsf(z)));
;           lk[jt] = (sk < tq) ? -sp : 0.f;
;           lb[jt] = z - sp;
;           float x = lk[jt];
;           x += dpp_f<0x101>(x); x += dpp_f<0x102>(x); x += dpp_f<0x104>(x); x += dpp_f<0x108>(x);
;           inc[jt] = x;
;           tot[jt] = grp16_sum_fast(lk[jt]);
;         }
;         float after = 0.f;
; #pragma unroll
;     ...
;           const int sk = kt * 64 + jt * 16 + fr;
;           const float e = lb[jt] + (inc[jt] - lk[jt]) + after + run[mt][j];
;           const float a = (sk < tq) ? __expf(e) : 0.f;
;           sP[(mt * 16 + fq * 4 + j) * VS + jt * 16 + fr] = f2bf(a);
;           after += tot[jt];
;         }
;         run[mt][j] += after;
.LBB0_428:
	s_or_b64 exec, exec, s[10:11]
	v_sub_f32_e32 v71, v46, v55
	v_sub_f32_e32 v46, v57, v59
	v_add_f32_e32 v57, v60, v61
	v_add_f32_e32 v60, v67, v68
	v_add_f32_e32 v56, v56, v58
	v_add_f32_e32 v58, v62, v63
	v_sub_f32_e32 v38, v38, v66
	v_add_f32_e32 v62, v72, v73
	v_add_f32_e32 v60, v66, v60
	v_add_f32_e32 v62, 0, v62
	v_add_f32_e32 v38, v38, v60
	v_add_f32_e32 v61, v69, v70
	v_add_f32_e32 v38, v38, v62
	v_add_f32_e32 v57, v59, v57
	v_mul_f32_e32 v38, 0x3fb8aa3b, v38
	v_add_f32_e32 v60, v61, v62
	v_add_f32_e32 v46, v46, v57
	v_exp_f32_e32 v38, v38
	v_add_f32_e32 v46, v46, v60
	v_mul_f32_e32 v46, 0x3fb8aa3b, v46
	v_exp_f32_e32 v46, v46
	v_cvt_pk_bf16_f32 v38, v38, s0
	v_cndmask_b32_e64 v38, 0, v38, s[4:5]
	v_add_f32_e32 v55, v55, v56
	ds_write_b16 v101, v38 offset:352
	v_cvt_pk_bf16_f32 v38, v46, s0
	v_add_f32_e32 v46, v58, v60
	v_add_f32_e32 v55, v71, v55
	v_add_f32_e32 v55, v55, v46
	v_mul_f32_e32 v47, 0x3db504f3, v47
	v_mul_f32_e32 v55, 0x3fb8aa3b, v55
	v_mul_f32_e64 v56, |v47|, s31
	v_exp_f32_e32 v55, v55
	v_exp_f32_e32 v56, v56
	v_cndmask_b32_e64 v38, 0, v38, s[0:1]
	ds_write_b16 v101, v38 offset:320
	v_cvt_pk_bf16_f32 v38, v55, s0
	v_add_f32_e32 v55, 1.0, v56
	s_nop 0
	v_cndmask_b32_e32 v38, 0, v38, vcc
	ds_write_b16 v101, v38 offset:288
	s_nop 0
	s_nop 0
	v_log_f32_e32 v55, v55
	v_max_f32_e32 v38, 0, v47
	v_mul_f32_e32 v39, 0x3db504f3, v39
	v_mul_f32_e32 v67, 0x3db504f3, v35
	v_mul_f32_e32 v56, 0x3f317217, v55
	v_fma_f32 v56, v55, s29, -v56
	v_fmac_f32_e32 v56, 0x3377d1cf, v55
	v_fmac_f32_e32 v56, 0x3f317217, v55
	s_nop 0
	v_mul_f32_e64 v35, |v67|, s31
	v_or_b32_e32 v103, 3, v100
	v_mov_b32_e32 v55, v56
	s_nop 0
	v_mov_b32_e32 v55, v55
	v_add_f32_e32 v38, v38, v55
	v_mul_f32_e32 v55, 0x3db504f3, v43
	v_mul_f32_e64 v43, |v55|, s31
	v_exp_f32_e32 v43, v43
	v_max_f32_e32 v59, 0, v55
	v_max_f32_e32 v69, 0, v67
	v_cmp_lt_i32_e32 vcc, v51, v103
	v_add_f32_e32 v43, 1.0, v43
	s_nop 0
	v_cndmask_b32_e64 v57, 0, -v38, vcc
	ds_write_b16 v101, v75 offset:384
	s_nop 0
	s_nop 0
	v_log_f32_e32 v43, v43
	v_add_f32_dpp v51, v57, v57 row_shl:1 row_mask:0xf bank_mask:0xf bound_ctrl:1
	v_add_f32_dpp v57, v57, v57 row_ror:8 row_mask:0xf bank_mask:0xf bound_ctrl:1
	v_mul_f32_e32 v60, 0x3f317217, v43
	v_fma_f32 v60, v43, s29, -v60
	v_fmac_f32_e32 v60, 0x3377d1cf, v43
	v_fmac_f32_e32 v60, 0x3f317217, v43
	s_nop 0
	v_add_f32_dpp v51, v51, v51 row_shl:2 row_mask:0xf bank_mask:0xf bound_ctrl:1
	v_add_f32_dpp v57, v57, v57 row_ror:4 row_mask:0xf bank_mask:0xf bound_ctrl:1
	v_mov_b32_e32 v43, v60
	s_nop 0
	v_mov_b32_e32 v43, v43
	v_add_f32_e32 v43, v59, v43
	v_mul_f32_e64 v59, |v39|, s31
	v_exp_f32_e32 v61, v59
	v_cmp_lt_i32_e64 s[0:1], v52, v103
	v_add_f32_dpp v51, v51, v51 row_shl:4 row_mask:0xf bank_mask:0xf bound_ctrl:1
	v_add_f32_dpp v57, v57, v57 row_ror:2 row_mask:0xf bank_mask:0xf bound_ctrl:1
	v_add_f32_e32 v61, 1.0, v61
	s_nop 0
	v_cndmask_b32_e64 v60, 0, -v43, s[0:1]
	v_mov_b32_dpp v56, v51 row_shl:8 row_mask:0xf bank_mask:0xf bound_ctrl:1
	s_nop 0
	s_nop 0
	v_log_f32_e32 v63, v61
	v_add_f32_dpp v52, v60, v60 row_shl:1 row_mask:0xf bank_mask:0xf bound_ctrl:1
	v_add_f32_dpp v60, v60, v60 row_ror:8 row_mask:0xf bank_mask:0xf bound_ctrl:1
	v_mov_b32_dpp v58, v57 row_ror:1 row_mask:0xf bank_mask:0xf bound_ctrl:1
	v_mul_f32_e32 v66, 0x3f317217, v63
	v_fma_f32 v66, v63, s29, -v66
	v_fmac_f32_e32 v66, 0x3377d1cf, v63
	v_fmac_f32_e32 v66, 0x3f317217, v63
	s_nop 0
	v_add_f32_dpp v60, v60, v60 row_ror:4 row_mask:0xf bank_mask:0xf bound_ctrl:1
	v_add_f32_dpp v52, v52, v52 row_shl:2 row_mask:0xf bank_mask:0xf bound_ctrl:1
	v_mov_b32_e32 v63, v66
	s_nop 0
	v_mov_b32_e32 v63, v63
	v_exp_f32_e32 v66, v35
	v_add_f32_dpp v61, v60, v60 row_ror:2 row_mask:0xf bank_mask:0xf bound_ctrl:1
	v_max_f32_e32 v60, 0, v39
	v_add_f32_e32 v60, v60, v63
	v_add_f32_e32 v66, 1.0, v66
	s_nop 0
	v_cmp_lt_i32_e64 s[6:7], v36, v103
	v_add_f32_dpp v52, v52, v52 row_shl:4 row_mask:0xf bank_mask:0xf bound_ctrl:1
	s_nop 0
	s_nop 0
	v_log_f32_e32 v68, v66
	v_cndmask_b32_e64 v63, 0, -v60, s[6:7]
	v_mov_b32_dpp v59, v52 row_shl:8 row_mask:0xf bank_mask:0xf bound_ctrl:1
	v_mov_b32_dpp v62, v61 row_ror:1 row_mask:0xf bank_mask:0xf bound_ctrl:1
	v_mul_f32_e32 v70, 0x3f317217, v68
	v_fma_f32 v70, v68, s29, -v70
	v_fmac_f32_e32 v70, 0x3377d1cf, v68
	v_fmac_f32_e32 v70, 0x3f317217, v68
	s_nop 0
	v_add_f32_dpp v36, v63, v63 row_shl:1 row_mask:0xf bank_mask:0xf bound_ctrl:1
	v_add_f32_dpp v63, v63, v63 row_ror:8 row_mask:0xf bank_mask:0xf bound_ctrl:1
	v_mov_b32_e32 v68, v70
	s_nop 0
	v_mov_b32_e32 v68, v68
	v_add_f32_e32 v69, v69, v68
	v_cmp_lt_i32_e64 s[4:5], v32, v103
	v_add_f32_dpp v36, v36, v36 row_shl:2 row_mask:0xf bank_mask:0xf bound_ctrl:1
	v_add_f32_dpp v63, v63, v63 row_ror:4 row_mask:0xf bank_mask:0xf bound_ctrl:1
	v_cndmask_b32_e64 v32, 0, -v69, s[4:5]
	v_add_f32_dpp v36, v36, v36 row_shl:4 row_mask:0xf bank_mask:0xf bound_ctrl:1
	v_add_f32_dpp v63, v63, v63 row_ror:2 row_mask:0xf bank_mask:0xf bound_ctrl:1
	v_add_f32_dpp v68, v32, v32 row_shl:1 row_mask:0xf bank_mask:0xf bound_ctrl:1
	v_add_f32_dpp v32, v32, v32 row_ror:8 row_mask:0xf bank_mask:0xf bound_ctrl:1
	v_mov_b32_dpp v35, v36 row_shl:8 row_mask:0xf bank_mask:0xf bound_ctrl:1
	v_add_f32_dpp v68, v68, v68 row_shl:2 row_mask:0xf bank_mask:0xf bound_ctrl:1
	v_add_f32_dpp v32, v32, v32 row_ror:4 row_mask:0xf bank_mask:0xf bound_ctrl:1
	v_mov_b32_dpp v66, v63 row_ror:1 row_mask:0xf bank_mask:0xf bound_ctrl:1
	v_add_f32_dpp v70, v68, v68 row_shl:4 row_mask:0xf bank_mask:0xf bound_ctrl:1
	v_add_f32_dpp v32, v32, v32 row_ror:2 row_mask:0xf bank_mask:0xf bound_ctrl:1
	s_nop 0
	v_mov_b32_dpp v71, v70 row_shl:8 row_mask:0xf bank_mask:0xf bound_ctrl:1
	v_mov_b32_dpp v68, v32 row_ror:1 row_mask:0xf bank_mask:0xf bound_ctrl:1
	s_and_saveexec_b64 s[10:11], s[4:5]
	s_cbranch_execz .LBB0_430
	v_add_f32_e32 v34, v70, v71
	v_sub_f32_e32 v67, v67, v69
	v_add_f32_e32 v34, v69, v34
	v_add_f32_e32 v34, v67, v34
	v_add_f32_e32 v34, 0, v34
	v_mul_f32_e32 v34, 0x3fb8aa3b, v34
	v_exp_f32_e32 v34, v34
	s_nop 0
	v_cvt_pk_bf16_f32 v34, v34, s0

; DEV f32x4 mfma16(bf16x8 a, bf16x8 b, f32x4 c) { return __builtin_amdgcn_mfma_f32_16x16x32_bf16(a, b, c, 0, 0, 0); }
; DEV void qk_tile(const bf16x8 (&qf)[MT][4], const u16* sK, f32x4 (&s)[MT][4], int fr, int fq) {
; #pragma unroll
;   for (int mt = 0; mt < MT; ++mt)
; #pragma unroll
;     for (int jt = 0; jt < 4; ++jt) s[mt][jt] = (f32x4){0.f, 0.f, 0.f, 0.f};
; #pragma unroll
;   for (int ks = 0; ks < 4; ++ks) {
;     bf16x8 b[4];
; #pragma unroll
;     for (int jt = 0; jt < 4; ++jt) b[jt] = *(const bf16x8*)(sK + (jt * 16 + fr) * KS + ks * 32 + fq * 8);
; #pragma unroll
;     for (int jt = 0; jt < 4; ++jt)
; #pragma unroll
;       for (int mt = 0; mt < MT; ++mt) s[mt][jt] = mfma16(qf[mt][ks], b[jt], s[mt][jt]);
;   }
; }
.LBB0_438:
	v_lshlrev_b32_e32 v64, 1, v94
	v_add3_u32 v83, s0, v108, v64
	ds_read_b128 v[64:67], v83
	ds_read_b128 v[68:71], v83 offset:4352
	ds_read_b128 v[72:75], v83 offset:8704
	ds_read_b128 v[76:79], v83 offset:13056
	ds_read_b128 v[112:115], v83 offset:64
	ds_read_b128 v[116:119], v83 offset:4416
	ds_read_b128 v[120:123], v83 offset:8768
	ds_read_b128 v[124:127], v83 offset:13120
	s_waitcnt lgkmcnt(7)
	v_mfma_f32_16x16x32_bf16 v[64:67], v[0:3], v[64:67], 0
	v_mov_b32_e32 v139, 0
	s_waitcnt lgkmcnt(6)
	v_mfma_f32_16x16x32_bf16 v[68:71], v[0:3], v[68:71], 0
	s_waitcnt lgkmcnt(5)
	v_mfma_f32_16x16x32_bf16 v[72:75], v[0:3], v[72:75], 0
	s_waitcnt lgkmcnt(4)
	v_mfma_f32_16x16x32_bf16 v[76:79], v[0:3], v[76:79], 0
	s_waitcnt lgkmcnt(3)
	v_mfma_f32_16x16x32_bf16 v[64:67], v[4:7], v[112:115], v[64:67]
	s_waitcnt lgkmcnt(2)
	v_mfma_f32_16x16x32_bf16 v[68:71], v[4:7], v[116:119], v[68:71]
	s_waitcnt lgkmcnt(1)
	v_mfma_f32_16x16x32_bf16 v[72:75], v[4:7], v[120:123], v[72:75]
	s_waitcnt lgkmcnt(0)
	v_mfma_f32_16x16x32_bf16 v[76:79], v[4:7], v[124:127], v[76:79]
	ds_read_b128 v[112:115], v83 offset:128
	ds_read_b128 v[116:119], v83 offset:4480
	ds_read_b128 v[120:123], v83 offset:8832
	ds_read_b128 v[124:127], v83 offset:13184
	s_waitcnt lgkmcnt(3)
	v_mfma_f32_16x16x32_bf16 v[64:67], v[8:11], v[112:115], v[64:67]
	s_waitcnt lgkmcnt(2)
	v_mfma_f32_16x16x32_bf16 v[68:71], v[8:11], v[116:119], v[68:71]
	s_waitcnt lgkmcnt(1)
	v_mfma_f32_16x16x32_bf16 v[112:115], v[8:11], v[120:123], v[72:75]
	s_waitcnt lgkmcnt(0)
	v_mfma_f32_16x16x32_bf16 v[116:119], v[8:11], v[124:127], v[76:79]
	s_nop 0
	ds_read_b128 v[72:75], v83 offset:192
	ds_read_b128 v[120:123], v83 offset:4544
	ds_read_b128 v[124:127], v83 offset:8896
	ds_read_b128 v[132:135], v83 offset:13248
	s_waitcnt lgkmcnt(3)
	v_mfma_f32_16x16x32_bf16 v[76:79], v[12:15], v[72:75], v[64:67]
	s_waitcnt lgkmcnt(2)
	v_mfma_f32_16x16x32_bf16 v[72:75], v[12:15], v[120:123], v[68:71]
	s_waitcnt lgkmcnt(1)
	v_mfma_f32_16x16x32_bf16 v[68:71], v[12:15], v[124:127], v[112:115]
	s_nop 3
	v_mul_f32_e32 v114, 0x3db504f3, v76
	v_mul_f32_e64 v83, |v114|, s31
	v_exp_f32_e32 v83, v83
	s_waitcnt lgkmcnt(0)
; DEV void sb_item(const Params& p, int item, unsigned char* smem) {
;     ...
;         const int tq = q0 + mt * 16 + fq * 4 + j;
;         float lk[4], lb[4], inc[4], tot[4];
; #pragma unroll
;         for (int jt = 0; jt < 4; ++jt) {
;           const int sk = kt * 64 + jt * 16 + fr;
;           const float z = s[mt][jt][j] * scale;
;           const float sp = fmaxf(z, 0.f) + __logf(1.0f + __expf(-fabsf(z)));
;           lk[jt] = (sk < tq) ? -sp : 0.f;
;           lb[jt] = z - sp;
;           float x = lk[jt];
;           x += dpp_f<0x101>(x); x += dpp_f<0x102>(x); x += dpp_f<0x104>(x); x += dpp_f<0x108>(x);
;           inc[jt] = x;
;           tot[jt] = grp16_sum_fast(lk[jt]);
;         }
;         float after = 0.f;
; #pragma unroll
;     ...
;           const int sk = kt * 64 + jt * 16 + fr;
;           const float e = lb[jt] + (inc[jt] - lk[jt]) + after + run[mt][j];
;           const float a = (sk < tq) ? __expf(e) : 0.f;
;           sP[(mt * 16 + fq * 4 + j) * VS + jt * 16 + fr] = f2bf(a);
;           after += tot[jt];
;         }
;         run[mt][j] += after;
	v_mfma_f32_16x16x32_bf16 v[64:67], v[12:15], v[132:135], v[116:119]
	v_mul_f32_e32 v124, 0x3db504f3, v68
	v_mul_f32_e64 v125, |v124|, s31
	v_add_f32_e32 v83, 1.0, v83
	s_nop 0
	v_mul_f32_e32 v118, 0x3db504f3, v72
	v_mul_f32_e64 v119, |v118|, s31
	s_nop 0
	s_nop 0
	v_log_f32_e32 v83, v83
	v_exp_f32_e32 v119, v119
	v_exp_f32_e32 v125, v125
	v_mul_f32_e32 v64, 0x3db504f3, v64
	v_mul_f32_e32 v113, 0x3f317217, v83
	v_fma_f32 v113, v83, s29, -v113
	v_fmac_f32_e32 v113, 0x3377d1cf, v83
	v_fmac_f32_e32 v113, 0x3f317217, v83
	s_nop 0
	v_add_f32_e32 v119, 1.0, v119
	v_add_f32_e32 v125, 1.0, v125
	v_mov_b32_e32 v83, v113
	s_nop 0
	v_mul_f32_e64 v134, |v64|, s31
	v_exp_f32_e32 v134, v134
	s_nop 0
	s_nop 0
	v_log_f32_e32 v119, v119
	v_add_f32_e32 v134, 1.0, v134
	v_add_u32_e32 v133, s44, v92
	s_nop 0
	v_mul_f32_e32 v120, 0x3f317217, v119
	v_fma_f32 v120, v119, s29, -v120
	v_fmac_f32_e32 v120, 0x3377d1cf, v119
	v_fmac_f32_e32 v120, 0x3f317217, v119
	s_nop 0
	v_mov_b32_e32 v83, v83
	v_add_u32_e32 v113, 0x50, v133
	v_mov_b32_e32 v119, v120
	s_nop 0
	s_nop 0
	v_max_f32_e32 v72, 0, v118
	s_nop 0
	s_nop 0
	v_log_f32_e32 v125, v125
	v_mov_b32_e32 v119, v119
	v_add_f32_e32 v121, v72, v119
	v_cmp_lt_i32_e64 s[0:1], v113, v100
	v_mul_f32_e32 v126, 0x3f317217, v125
	v_fma_f32 v126, v125, s29, -v126
	v_fmac_f32_e32 v126, 0x3377d1cf, v125
	v_fmac_f32_e32 v126, 0x3f317217, v125
	s_nop 0
	v_cndmask_b32_e64 v72, 0, -v121, s[0:1]
	v_max_f32_e32 v68, 0, v124
	v_mov_b32_e32 v125, v126
	s_nop 0
	v_add_f32_dpp v119, v72, v72 row_shl:1 row_mask:0xf bank_mask:0xf bound_ctrl:1
	v_add_f32_dpp v72, v72, v72 row_ror:8 row_mask:0xf bank_mask:0xf bound_ctrl:1
	s_nop 0
	s_nop 0
	v_log_f32_e32 v134, v134
	v_add_f32_dpp v119, v119, v119 row_shl:2 row_mask:0xf bank_mask:0xf bound_ctrl:1
	v_add_f32_dpp v72, v72, v72 row_ror:4 row_mask:0xf bank_mask:0xf bound_ctrl:1
	s_nop 0
	v_add_f32_dpp v122, v119, v119 row_shl:4 row_mask:0xf bank_mask:0xf bound_ctrl:1
	v_add_f32_dpp v119, v72, v72 row_ror:2 row_mask:0xf bank_mask:0xf bound_ctrl:1
	v_add_u32_e32 v72, 0x60, v133
	v_mov_b32_e32 v125, v125
	v_mul_f32_e32 v135, 0x3f317217, v134
	v_add_f32_e32 v127, v68, v125
	v_cmp_lt_i32_e64 s[10:11], v72, v100
	v_fma_f32 v135, v134, s29, -v135
	v_fmac_f32_e32 v135, 0x3377d1cf, v134
	v_cndmask_b32_e64 v68, 0, -v127, s[10:11]
	v_fmac_f32_e32 v135, 0x3f317217, v134
	s_nop 0
	v_add_f32_dpp v125, v68, v68 row_shl:1 row_mask:0xf bank_mask:0xf bound_ctrl:1
	v_add_f32_dpp v68, v68, v68 row_ror:8 row_mask:0xf bank_mask:0xf bound_ctrl:1
	v_mov_b32_e32 v134, v135
	v_add_f32_dpp v125, v125, v125 row_shl:2 row_mask:0xf bank_mask:0xf bound_ctrl:1
	v_add_f32_dpp v68, v68, v68 row_ror:4 row_mask:0xf bank_mask:0xf bound_ctrl:1
	s_nop 0
	v_add_u32_e32 v112, 64, v133
	v_max_f32_e32 v76, 0, v114
	v_add_f32_dpp v131, v125, v125 row_shl:4 row_mask:0xf bank_mask:0xf bound_ctrl:1
	v_add_f32_dpp v125, v68, v68 row_ror:2 row_mask:0xf bank_mask:0xf bound_ctrl:1
	v_add_u32_e32 v68, 0x70, v133
	v_max_f32_e32 v133, 0, v64
	v_mov_b32_e32 v134, v134
	v_add_f32_e32 v115, v76, v83
	v_cmp_lt_i32_e32 vcc, v112, v100
	v_add_f32_e32 v136, v133, v134
	v_cmp_lt_i32_e64 s[14:15], v68, v100
	v_cndmask_b32_e64 v76, 0, -v115, vcc
	v_mov_b32_dpp v123, v122 row_shl:8 row_mask:0xf bank_mask:0xf bound_ctrl:1
	v_cndmask_b32_e64 v133, 0, -v136, s[14:15]
	v_add_f32_dpp v83, v76, v76 row_shl:1 row_mask:0xf bank_mask:0xf bound_ctrl:1
	v_add_f32_dpp v76, v76, v76 row_ror:8 row_mask:0xf bank_mask:0xf bound_ctrl:1
	v_add_f32_dpp v134, v133, v133 row_shl:1 row_mask:0xf bank_mask:0xf bound_ctrl:1
	v_add_f32_dpp v133, v133, v133 row_ror:8 row_mask:0xf bank_mask:0xf bound_ctrl:1
	v_add_f32_dpp v83, v83, v83 row_shl:2 row_mask:0xf bank_mask:0xf bound_ctrl:1
	v_add_f32_dpp v76, v76, v76 row_ror:4 row_mask:0xf bank_mask:0xf bound_ctrl:1
	v_add_f32_dpp v134, v134, v134 row_shl:2 row_mask:0xf bank_mask:0xf bound_ctrl:1
	v_add_f32_dpp v133, v133, v133 row_ror:4 row_mask:0xf bank_mask:0xf bound_ctrl:1
	v_add_f32_dpp v116, v83, v83 row_shl:4 row_mask:0xf bank_mask:0xf bound_ctrl:1
	v_add_f32_dpp v76, v76, v76 row_ror:2 row_mask:0xf bank_mask:0xf bound_ctrl:1
	v_add_f32_dpp v137, v134, v134 row_shl:4 row_mask:0xf bank_mask:0xf bound_ctrl:1
	v_add_f32_dpp v134, v133, v133 row_ror:2 row_mask:0xf bank_mask:0xf bound_ctrl:1
	v_mov_b32_dpp v117, v116 row_shl:8 row_mask:0xf bank_mask:0xf bound_ctrl:1
	v_mov_b32_dpp v83, v76 row_ror:1 row_mask:0xf bank_mask:0xf bound_ctrl:1
	v_mov_b32_dpp v120, v119 row_ror:1 row_mask:0xf bank_mask:0xf bound_ctrl:1
	v_mov_b32_dpp v132, v131 row_shl:8 row_mask:0xf bank_mask:0xf bound_ctrl:1
	v_mov_b32_dpp v126, v125 row_ror:1 row_mask:0xf bank_mask:0xf bound_ctrl:1
	v_mov_b32_dpp v138, v137 row_shl:8 row_mask:0xf bank_mask:0xf bound_ctrl:1
	v_mov_b32_dpp v135, v134 row_ror:1 row_mask:0xf bank_mask:0xf bound_ctrl:1
	v_mov_b32_e32 v133, 0
	s_and_saveexec_b64 s[16:17], s[14:15]
	s_cbranch_execz .LBB0_440
	v_add_f32_e32 v137, v137, v138
	v_sub_f32_e32 v64, v64, v136
	v_add_f32_e32 v136, v136, v137
	v_add_f32_e32 v64, v64, v136
	v_add_f32_e32 v64, 0, v64
	v_add_f32_e32 v64, v106, v64
	v_mul_f32_e32 v64, 0x3fb8aa3b, v64
	v_exp_f32_e32 v64, v64
	s_nop 0
	v_cvt_pk_bf16_f32 v139, v64, s0

; DEV void sb_item(const Params& p, int item, unsigned char* smem) {
;     ...
;           const int sk = kt * 64 + jt * 16 + fr;
;           const float z = s[mt][jt][j] * scale;
;           const float sp = fmaxf(z, 0.f) + __logf(1.0f + __expf(-fabsf(z)));
;           lk[jt] = (sk < tq) ? -sp : 0.f;
;           lb[jt] = z - sp;
;           float x = lk[jt];
;           x += dpp_f<0x101>(x); x += dpp_f<0x102>(x); x += dpp_f<0x104>(x); x += dpp_f<0x108>(x);
;           inc[jt] = x;
;           tot[jt] = grp16_sum_fast(lk[jt]);
;         }
;         float after = 0.f;
; #pragma unroll
;     ...
;           const int sk = kt * 64 + jt * 16 + fr;
;           const float e = lb[jt] + (inc[jt] - lk[jt]) + after + run[mt][j];
;           const float a = (sk < tq) ? __expf(e) : 0.f;
;           sP[(mt * 16 + fq * 4 + j) * VS + jt * 16 + fr] = f2bf(a);
.LBB0_446:
	s_or_b64 exec, exec, s[0:1]
	v_mul_f32_e32 v118, 0x3db504f3, v73
	v_mul_f32_e64 v73, |v118|, s31
	v_exp_f32_e32 v73, v73
	v_mul_f32_e32 v123, 0x3db504f3, v69
	v_mul_f32_e64 v69, |v123|, s31
	v_exp_f32_e32 v69, v69
	v_add_f32_e32 v73, 1.0, v73
	v_cmp_gt_f32_e64 s[0:1], s84, v73
	ds_write_b16 v101, v124
	v_add_f32_e32 v69, 1.0, v69
	v_cndmask_b32_e64 v119, 0, 32, s[0:1]
	v_ldexp_f32 v73, v73, v119
	v_log_f32_e32 v119, v73
	v_mul_f32_e32 v114, 0x3db504f3, v77
	v_mul_f32_e32 v131, 0x3db504f3, v65
	v_mul_f32_e64 v77, |v114|, s31
	v_mul_f32_e32 v121, 0x3f317217, v119
	v_fma_f32 v121, v119, s29, -v121
	v_fmac_f32_e32 v121, 0x3377d1cf, v119
	v_fmac_f32_e32 v121, 0x3f317217, v119
	v_cmp_lt_f32_e64 s[10:11], |v119|, s36
	v_mul_f32_e64 v65, |v131|, s31
	v_exp_f32_e32 v77, v77
	v_cndmask_b32_e64 v119, v119, v121, s[10:11]
	s_nop 0
	v_exp_f32_e32 v65, v65
	v_add_f32_e32 v77, 1.0, v77
	s_nop 0
	s_nop 0
	v_log_f32_e32 v124, v69
	v_add_f32_e32 v65, 1.0, v65
	s_nop 0
	v_cndmask_b32_e64 v121, 0, v171, s[0:1]
	v_mul_f32_e32 v126, 0x3f317217, v124
	v_fma_f32 v126, v124, s29, -v126
	v_fmac_f32_e32 v126, 0x3377d1cf, v124
	v_fmac_f32_e32 v126, 0x3f317217, v124
	s_nop 0
	s_nop 0
	s_nop 0
	v_mov_b32_e32 v124, v126
	s_nop 0
	v_log_f32_e32 v77, v77
	s_nop 0
	s_nop 0
	s_nop 0
	v_log_f32_e32 v132, v65
	v_mul_f32_e32 v117, 0x3f317217, v77
	v_fma_f32 v117, v77, s29, -v117
	v_fmac_f32_e32 v117, 0x3377d1cf, v77
	v_mul_f32_e32 v134, 0x3f317217, v132
	v_fma_f32 v134, v132, s29, -v134
	v_fmac_f32_e32 v134, 0x3377d1cf, v132
	v_fmac_f32_e32 v117, 0x3f317217, v77
	s_nop 0
	v_fmac_f32_e32 v134, 0x3f317217, v132
	s_nop 0
	v_mov_b32_e32 v77, v117
	s_nop 0
	v_mov_b32_e32 v132, v134
	s_nop 0
	v_max_f32_e32 v115, 0, v114
	v_mov_b32_e32 v77, v77
	v_max_f32_e32 v120, 0, v118
	v_sub_f32_e32 v119, v119, v121
	v_max_f32_e32 v125, 0, v123
	v_mov_b32_e32 v124, v124
	v_max_f32_e32 v133, 0, v131
	v_mov_b32_e32 v132, v132
	v_add_f32_e32 v115, v115, v77
	v_cmp_le_i32_e32 vcc, v112, v100
	v_add_f32_e32 v119, v120, v119
	v_cmp_le_i32_e64 s[0:1], v113, v100
	v_add_f32_e32 v124, v125, v124
	v_cmp_le_i32_e64 s[10:11], v72, v100
	v_add_f32_e32 v135, v133, v132
	v_cmp_le_i32_e64 s[14:15], v68, v100
	v_cndmask_b32_e64 v77, 0, -v115, vcc
	v_cndmask_b32_e64 v121, 0, -v119, s[0:1]
	v_cndmask_b32_e64 v126, 0, -v124, s[10:11]
	v_cndmask_b32_e64 v132, 0, -v135, s[14:15]
	v_add_f32_dpp v116, v77, v77 row_shl:1 row_mask:0xf bank_mask:0xf bound_ctrl:1
	v_add_f32_dpp v77, v77, v77 row_ror:8 row_mask:0xf bank_mask:0xf bound_ctrl:1
	v_add_f32_dpp v120, v121, v121 row_shl:1 row_mask:0xf bank_mask:0xf bound_ctrl:1
	v_add_f32_dpp v121, v121, v121 row_ror:8 row_mask:0xf bank_mask:0xf bound_ctrl:1
	v_add_f32_dpp v125, v126, v126 row_shl:1 row_mask:0xf bank_mask:0xf bound_ctrl:1
	v_add_f32_dpp v126, v126, v126 row_ror:8 row_mask:0xf bank_mask:0xf bound_ctrl:1
	v_add_f32_dpp v133, v132, v132 row_shl:1 row_mask:0xf bank_mask:0xf bound_ctrl:1
	v_add_f32_dpp v132, v132, v132 row_ror:8 row_mask:0xf bank_mask:0xf bound_ctrl:1
	v_add_f32_dpp v116, v116, v116 row_shl:2 row_mask:0xf bank_mask:0xf bound_ctrl:1
	v_add_f32_dpp v77, v77, v77 row_ror:4 row_mask:0xf bank_mask:0xf bound_ctrl:1
	v_add_f32_dpp v120, v120, v120 row_shl:2 row_mask:0xf bank_mask:0xf bound_ctrl:1
	v_add_f32_dpp v121, v121, v121 row_ror:4 row_mask:0xf bank_mask:0xf bound_ctrl:1
	v_add_f32_dpp v125, v125, v125 row_shl:2 row_mask:0xf bank_mask:0xf bound_ctrl:1
	v_add_f32_dpp v126, v126, v126 row_ror:4 row_mask:0xf bank_mask:0xf bound_ctrl:1
	v_add_f32_dpp v133, v133, v133 row_shl:2 row_mask:0xf bank_mask:0xf bound_ctrl:1
	v_add_f32_dpp v132, v132, v132 row_ror:4 row_mask:0xf bank_mask:0xf bound_ctrl:1
	v_add_f32_dpp v116, v116, v116 row_shl:4 row_mask:0xf bank_mask:0xf bound_ctrl:1
	v_add_f32_dpp v73, v77, v77 row_ror:2 row_mask:0xf bank_mask:0xf bound_ctrl:1
	v_add_f32_dpp v120, v120, v120 row_shl:4 row_mask:0xf bank_mask:0xf bound_ctrl:1
	v_add_f32_dpp v69, v121, v121 row_ror:2 row_mask:0xf bank_mask:0xf bound_ctrl:1
	v_add_f32_dpp v125, v125, v125 row_shl:4 row_mask:0xf bank_mask:0xf bound_ctrl:1
	v_add_f32_dpp v65, v126, v126 row_ror:2 row_mask:0xf bank_mask:0xf bound_ctrl:1
	v_add_f32_dpp v136, v133, v133 row_shl:4 row_mask:0xf bank_mask:0xf bound_ctrl:1
	v_add_f32_dpp v133, v132, v132 row_ror:2 row_mask:0xf bank_mask:0xf bound_ctrl:1
	v_mov_b32_dpp v117, v116 row_shl:8 row_mask:0xf bank_mask:0xf bound_ctrl:1
	v_mov_b32_dpp v77, v73 row_ror:1 row_mask:0xf bank_mask:0xf bound_ctrl:1
	v_mov_b32_dpp v122, v120 row_shl:8 row_mask:0xf bank_mask:0xf bound_ctrl:1
	v_mov_b32_dpp v121, v69 row_ror:1 row_mask:0xf bank_mask:0xf bound_ctrl:1
	v_mov_b32_dpp v127, v125 row_shl:8 row_mask:0xf bank_mask:0xf bound_ctrl:1
	v_mov_b32_dpp v126, v65 row_ror:1 row_mask:0xf bank_mask:0xf bound_ctrl:1
	v_mov_b32_dpp v137, v136 row_shl:8 row_mask:0xf bank_mask:0xf bound_ctrl:1
	v_mov_b32_dpp v134, v133 row_ror:1 row_mask:0xf bank_mask:0xf bound_ctrl:1
	v_mov_b32_e32 v132, 0
	v_mov_b32_e32 v138, 0
	s_and_saveexec_b64 s[16:17], s[14:15]
	s_cbranch_execz .LBB0_448
	v_add_f32_e32 v136, v136, v137
	v_sub_f32_e32 v131, v131, v135
	v_add_f32_e32 v135, v135, v136
	v_add_f32_e32 v131, v131, v135
	v_add_f32_e32 v131, 0, v131
	v_add_f32_e32 v131, v105, v131
	v_mul_f32_e32 v131, 0x3fb8aa3b, v131
	v_exp_f32_e32 v131, v131
	s_nop 0
	v_cvt_pk_bf16_f32 v138, v131, s0

; DEV void sb_item(const Params& p, int item, unsigned char* smem) {
;     ...
;           const int sk = kt * 64 + jt * 16 + fr;
;           const float z = s[mt][jt][j] * scale;
;           const float sp = fmaxf(z, 0.f) + __logf(1.0f + __expf(-fabsf(z)));
;           lk[jt] = (sk < tq) ? -sp : 0.f;
;           lb[jt] = z - sp;
;           float x = lk[jt];
;           x += dpp_f<0x101>(x); x += dpp_f<0x102>(x); x += dpp_f<0x104>(x); x += dpp_f<0x108>(x);
;           inc[jt] = x;
;           tot[jt] = grp16_sum_fast(lk[jt]);
;         }
;         float after = 0.f;
; #pragma unroll
;     ...
;           const int sk = kt * 64 + jt * 16 + fr;
;           const float e = lb[jt] + (inc[jt] - lk[jt]) + after + run[mt][j];
;           const float a = (sk < tq) ? __expf(e) : 0.f;
;           sP[(mt * 16 + fq * 4 + j) * VS + jt * 16 + fr] = f2bf(a);
.LBB0_454:
	s_or_b64 exec, exec, s[0:1]
	v_mul_f32_e32 v117, 0x3db504f3, v74
	v_mul_f32_e64 v74, |v117|, s31
	v_exp_f32_e32 v74, v74
	v_mul_f32_e32 v122, 0x3db504f3, v70
	v_mul_f32_e64 v70, |v122|, s31
	v_exp_f32_e32 v70, v70
	v_add_f32_e32 v74, 1.0, v74
	v_cmp_gt_f32_e64 s[0:1], s84, v74
	ds_write_b16 v101, v123 offset:144
	v_add_f32_e32 v70, 1.0, v70
	v_cndmask_b32_e64 v118, 0, 32, s[0:1]
	v_ldexp_f32 v74, v74, v118
	v_log_f32_e32 v118, v74
	v_mul_f32_e32 v78, 0x3db504f3, v78
	v_mul_f32_e32 v127, 0x3db504f3, v66
	v_mul_f32_e64 v69, |v78|, s31
	v_mul_f32_e32 v120, 0x3f317217, v118
	v_fma_f32 v120, v118, s29, -v120
	v_fmac_f32_e32 v120, 0x3377d1cf, v118
	v_fmac_f32_e32 v120, 0x3f317217, v118
	v_cmp_lt_f32_e64 s[10:11], |v118|, s36
	v_mul_f32_e64 v66, |v127|, s31
	v_exp_f32_e32 v69, v69
	v_cndmask_b32_e64 v118, v118, v120, s[10:11]
	s_nop 0
	v_exp_f32_e32 v66, v66
	v_add_f32_e32 v69, 1.0, v69
	s_nop 0
	s_nop 0
	v_log_f32_e32 v123, v70
	v_add_f32_e32 v66, 1.0, v66
	s_nop 0
	v_cndmask_b32_e64 v120, 0, v171, s[0:1]
	v_mul_f32_e32 v125, 0x3f317217, v123
	v_fma_f32 v125, v123, s29, -v125
	v_fmac_f32_e32 v125, 0x3377d1cf, v123
	v_fmac_f32_e32 v125, 0x3f317217, v123
	s_nop 0
	s_nop 0
	s_nop 0
	v_mov_b32_e32 v123, v125
	s_nop 0
	v_log_f32_e32 v69, v69
	s_nop 0
	s_nop 0
	s_nop 0
	v_log_f32_e32 v131, v66
	v_mul_f32_e32 v116, 0x3f317217, v69
	v_fma_f32 v116, v69, s29, -v116
	v_fmac_f32_e32 v116, 0x3377d1cf, v69
	v_mul_f32_e32 v133, 0x3f317217, v131
	v_fma_f32 v133, v131, s29, -v133
	v_fmac_f32_e32 v133, 0x3377d1cf, v131
	v_fmac_f32_e32 v116, 0x3f317217, v69
	s_nop 0
	v_fmac_f32_e32 v133, 0x3f317217, v131
	s_nop 0
	v_mov_b32_e32 v69, v116
	s_nop 0
	v_mov_b32_e32 v131, v133
	s_nop 0
	v_max_f32_e32 v114, 0, v78
	v_mov_b32_e32 v69, v69
	v_max_f32_e32 v119, 0, v117
	v_sub_f32_e32 v118, v118, v120
	v_max_f32_e32 v124, 0, v122
	v_mov_b32_e32 v123, v123
	v_max_f32_e32 v132, 0, v127
	v_mov_b32_e32 v131, v131
	v_add_f32_e32 v114, v114, v69
	v_cmp_lt_i32_e32 vcc, v112, v102
	v_add_f32_e32 v118, v119, v118
	v_cmp_lt_i32_e64 s[0:1], v113, v102
	v_add_f32_e32 v123, v124, v123
	v_cmp_lt_i32_e64 s[10:11], v72, v102
	v_add_f32_e32 v134, v132, v131
	v_cmp_lt_i32_e64 s[14:15], v68, v102
	v_cndmask_b32_e64 v69, 0, -v114, vcc
	v_cndmask_b32_e64 v120, 0, -v118, s[0:1]
	v_cndmask_b32_e64 v125, 0, -v123, s[10:11]
	v_cndmask_b32_e64 v131, 0, -v134, s[14:15]
	v_add_f32_dpp v115, v69, v69 row_shl:1 row_mask:0xf bank_mask:0xf bound_ctrl:1
	v_add_f32_dpp v69, v69, v69 row_ror:8 row_mask:0xf bank_mask:0xf bound_ctrl:1
	v_add_f32_dpp v119, v120, v120 row_shl:1 row_mask:0xf bank_mask:0xf bound_ctrl:1
	v_add_f32_dpp v120, v120, v120 row_ror:8 row_mask:0xf bank_mask:0xf bound_ctrl:1
	v_add_f32_dpp v124, v125, v125 row_shl:1 row_mask:0xf bank_mask:0xf bound_ctrl:1
	v_add_f32_dpp v125, v125, v125 row_ror:8 row_mask:0xf bank_mask:0xf bound_ctrl:1
	v_add_f32_dpp v132, v131, v131 row_shl:1 row_mask:0xf bank_mask:0xf bound_ctrl:1
	v_add_f32_dpp v131, v131, v131 row_ror:8 row_mask:0xf bank_mask:0xf bound_ctrl:1
	v_add_f32_dpp v115, v115, v115 row_shl:2 row_mask:0xf bank_mask:0xf bound_ctrl:1
	v_add_f32_dpp v69, v69, v69 row_ror:4 row_mask:0xf bank_mask:0xf bound_ctrl:1
	v_add_f32_dpp v119, v119, v119 row_shl:2 row_mask:0xf bank_mask:0xf bound_ctrl:1
	v_add_f32_dpp v120, v120, v120 row_ror:4 row_mask:0xf bank_mask:0xf bound_ctrl:1
	v_add_f32_dpp v124, v124, v124 row_shl:2 row_mask:0xf bank_mask:0xf bound_ctrl:1
	v_add_f32_dpp v125, v125, v125 row_ror:4 row_mask:0xf bank_mask:0xf bound_ctrl:1
	v_add_f32_dpp v132, v132, v132 row_shl:2 row_mask:0xf bank_mask:0xf bound_ctrl:1
	v_add_f32_dpp v131, v131, v131 row_ror:4 row_mask:0xf bank_mask:0xf bound_ctrl:1
	v_add_f32_dpp v115, v115, v115 row_shl:4 row_mask:0xf bank_mask:0xf bound_ctrl:1
	v_add_f32_dpp v69, v69, v69 row_ror:2 row_mask:0xf bank_mask:0xf bound_ctrl:1
	v_add_f32_dpp v119, v119, v119 row_shl:4 row_mask:0xf bank_mask:0xf bound_ctrl:1
	v_add_f32_dpp v70, v120, v120 row_ror:2 row_mask:0xf bank_mask:0xf bound_ctrl:1
	v_add_f32_dpp v124, v124, v124 row_shl:4 row_mask:0xf bank_mask:0xf bound_ctrl:1
	v_add_f32_dpp v66, v125, v125 row_ror:2 row_mask:0xf bank_mask:0xf bound_ctrl:1
	v_add_f32_dpp v135, v132, v132 row_shl:4 row_mask:0xf bank_mask:0xf bound_ctrl:1
	v_add_f32_dpp v132, v131, v131 row_ror:2 row_mask:0xf bank_mask:0xf bound_ctrl:1
	v_mov_b32_dpp v116, v115 row_shl:8 row_mask:0xf bank_mask:0xf bound_ctrl:1
	v_mov_b32_dpp v74, v69 row_ror:1 row_mask:0xf bank_mask:0xf bound_ctrl:1
	v_mov_b32_dpp v121, v119 row_shl:8 row_mask:0xf bank_mask:0xf bound_ctrl:1
	v_mov_b32_dpp v120, v70 row_ror:1 row_mask:0xf bank_mask:0xf bound_ctrl:1
	v_mov_b32_dpp v126, v124 row_shl:8 row_mask:0xf bank_mask:0xf bound_ctrl:1
	v_mov_b32_dpp v125, v66 row_ror:1 row_mask:0xf bank_mask:0xf bound_ctrl:1
	v_mov_b32_dpp v136, v135 row_shl:8 row_mask:0xf bank_mask:0xf bound_ctrl:1
	v_mov_b32_dpp v133, v132 row_ror:1 row_mask:0xf bank_mask:0xf bound_ctrl:1
	v_mov_b32_e32 v131, 0
	v_mov_b32_e32 v137, 0
	s_and_saveexec_b64 s[16:17], s[14:15]
	s_cbranch_execz .LBB0_456
	v_add_f32_e32 v135, v135, v136
	v_sub_f32_e32 v127, v127, v134
	v_add_f32_e32 v134, v134, v135
	v_add_f32_e32 v127, v127, v134
	v_add_f32_e32 v127, 0, v127
	v_add_f32_e32 v127, v104, v127
	v_mul_f32_e32 v127, 0x3fb8aa3b, v127
	v_exp_f32_e32 v127, v127
	s_nop 0
	v_cvt_pk_bf16_f32 v137, v127, s0

; DEV void sb_item(const Params& p, int item, unsigned char* smem) {
;     ...
;           const int sk = kt * 64 + jt * 16 + fr;
;           const float z = s[mt][jt][j] * scale;
;           const float sp = fmaxf(z, 0.f) + __logf(1.0f + __expf(-fabsf(z)));
;           lk[jt] = (sk < tq) ? -sp : 0.f;
;           lb[jt] = z - sp;
;           float x = lk[jt];
;           x += dpp_f<0x101>(x); x += dpp_f<0x102>(x); x += dpp_f<0x104>(x); x += dpp_f<0x108>(x);
;           inc[jt] = x;
;           tot[jt] = grp16_sum_fast(lk[jt]);
;         }
;         float after = 0.f;
; #pragma unroll
;     ...
;           const int sk = kt * 64 + jt * 16 + fr;
;           const float e = lb[jt] + (inc[jt] - lk[jt]) + after + run[mt][j];
;           const float a = (sk < tq) ? __expf(e) : 0.f;
;           sP[(mt * 16 + fq * 4 + j) * VS + jt * 16 + fr] = f2bf(a);
.LBB0_462:
	s_or_b64 exec, exec, s[0:1]
	v_mul_f32_e32 v70, 0x3db504f3, v79
	v_mul_f32_e64 v78, |v70|, s31
	v_exp_f32_e32 v78, v78
	v_mul_f32_e32 v119, 0x3db504f3, v71
	v_mul_f32_e64 v71, |v119|, s31
	v_exp_f32_e32 v71, v71
	v_add_f32_e32 v78, 1.0, v78
	s_nop 0
	v_mul_f32_e32 v123, 0x3db504f3, v67
	v_add_f32_e32 v71, 1.0, v71
	s_nop 0
	s_nop 0
	v_log_f32_e32 v78, v78
	s_nop 0
	v_mul_f32_e64 v67, |v123|, s31
	v_exp_f32_e32 v67, v67
	v_mul_f32_e32 v115, 0x3f317217, v78
	v_fma_f32 v115, v78, s29, -v115
	v_fmac_f32_e32 v115, 0x3377d1cf, v78
	v_fmac_f32_e32 v115, 0x3f317217, v78
	s_nop 0
	ds_write_b16 v101, v122 offset:288
	v_add_f32_e32 v67, 1.0, v67
	v_mov_b32_e32 v78, v115
	v_mul_f32_e32 v115, 0x3db504f3, v75
	v_mul_f32_e64 v75, |v115|, s31
	v_exp_f32_e32 v75, v75
	v_max_f32_e32 v79, 0, v70
	v_mov_b32_e32 v78, v78
	v_max_f32_e32 v117, 0, v115
	v_add_f32_e32 v75, 1.0, v75
	s_nop 0
	v_max_f32_e32 v121, 0, v119
	v_max_f32_e32 v125, 0, v123
	s_nop 0
	s_nop 0
	v_log_f32_e32 v116, v75
	v_add_f32_e32 v78, v79, v78
	v_cmp_lt_i32_e32 vcc, v112, v103
	v_mov_b32_e32 v132, 0
	v_mul_f32_e32 v118, 0x3f317217, v116
	v_fma_f32 v118, v116, s29, -v118
	v_fmac_f32_e32 v118, 0x3377d1cf, v116
	v_fmac_f32_e32 v118, 0x3f317217, v116
	s_nop 0
	v_cndmask_b32_e64 v112, 0, -v78, vcc
	s_nop 0
	v_mov_b32_e32 v116, v118
	v_cmp_gt_f32_e64 s[10:11], s84, v71
	s_nop 0
	v_mov_b32_e32 v116, v116
	v_cndmask_b32_e64 v120, 0, 32, s[10:11]
	v_ldexp_f32 v71, v71, v120
	v_log_f32_e32 v120, v71
	v_add_f32_e32 v116, v117, v116
	v_cmp_lt_i32_e64 s[0:1], v113, v103
	v_add_f32_dpp v79, v112, v112 row_shl:1 row_mask:0xf bank_mask:0xf bound_ctrl:1
	v_mul_f32_e32 v122, 0x3f317217, v120
	v_fma_f32 v122, v120, s29, -v122
	v_fmac_f32_e32 v122, 0x3377d1cf, v120
	v_fmac_f32_e32 v122, 0x3f317217, v120
	v_cmp_lt_f32_e64 s[14:15], |v120|, s36
	v_cndmask_b32_e64 v117, 0, -v116, s[0:1]
	v_add_f32_dpp v112, v112, v112 row_ror:8 row_mask:0xf bank_mask:0xf bound_ctrl:1
	v_cndmask_b32_e64 v120, v120, v122, s[14:15]
	v_cmp_gt_f32_e64 s[14:15], s84, v67
	v_cndmask_b32_e64 v122, 0, v171, s[10:11]
	v_sub_f32_e32 v120, v120, v122
	v_cndmask_b32_e64 v124, 0, 32, s[14:15]
	v_ldexp_f32 v67, v67, v124
	v_log_f32_e32 v124, v67
	v_add_f32_e32 v120, v121, v120
	v_cmp_lt_i32_e64 s[10:11], v72, v103
	v_add_f32_dpp v113, v117, v117 row_shl:1 row_mask:0xf bank_mask:0xf bound_ctrl:1
	v_mul_f32_e32 v126, 0x3f317217, v124
	v_fma_f32 v126, v124, s29, -v126
	v_fmac_f32_e32 v126, 0x3377d1cf, v124
	v_fmac_f32_e32 v126, 0x3f317217, v124
	v_cmp_lt_f32_e64 s[16:17], |v124|, s36
	v_cndmask_b32_e64 v121, 0, -v120, s[10:11]
	v_add_f32_dpp v117, v117, v117 row_ror:8 row_mask:0xf bank_mask:0xf bound_ctrl:1
	v_cndmask_b32_e64 v124, v124, v126, s[16:17]
	v_cndmask_b32_e64 v126, 0, v171, s[14:15]
	v_sub_f32_e32 v124, v124, v126
	v_add_f32_e32 v126, v125, v124
	v_cmp_lt_i32_e64 s[14:15], v68, v103
	v_add_f32_dpp v72, v121, v121 row_shl:1 row_mask:0xf bank_mask:0xf bound_ctrl:1
	v_add_f32_dpp v121, v121, v121 row_ror:8 row_mask:0xf bank_mask:0xf bound_ctrl:1
	v_cndmask_b32_e64 v68, 0, -v126, s[14:15]
	v_add_f32_dpp v79, v79, v79 row_shl:2 row_mask:0xf bank_mask:0xf bound_ctrl:1
	v_add_f32_dpp v112, v112, v112 row_ror:4 row_mask:0xf bank_mask:0xf bound_ctrl:1
	v_add_f32_dpp v124, v68, v68 row_shl:1 row_mask:0xf bank_mask:0xf bound_ctrl:1
	v_add_f32_dpp v68, v68, v68 row_ror:8 row_mask:0xf bank_mask:0xf bound_ctrl:1
	v_add_f32_dpp v113, v113, v113 row_shl:2 row_mask:0xf bank_mask:0xf bound_ctrl:1
	v_add_f32_dpp v117, v117, v117 row_ror:4 row_mask:0xf bank_mask:0xf bound_ctrl:1
	v_add_f32_dpp v72, v72, v72 row_shl:2 row_mask:0xf bank_mask:0xf bound_ctrl:1
	v_add_f32_dpp v121, v121, v121 row_ror:4 row_mask:0xf bank_mask:0xf bound_ctrl:1
	v_add_f32_dpp v124, v124, v124 row_shl:2 row_mask:0xf bank_mask:0xf bound_ctrl:1
	v_add_f32_dpp v68, v68, v68 row_ror:4 row_mask:0xf bank_mask:0xf bound_ctrl:1
	v_add_f32_dpp v79, v79, v79 row_shl:4 row_mask:0xf bank_mask:0xf bound_ctrl:1
	v_add_f32_dpp v75, v112, v112 row_ror:2 row_mask:0xf bank_mask:0xf bound_ctrl:1
	v_add_f32_dpp v113, v113, v113 row_shl:4 row_mask:0xf bank_mask:0xf bound_ctrl:1
	v_add_f32_dpp v71, v117, v117 row_ror:2 row_mask:0xf bank_mask:0xf bound_ctrl:1
	v_add_f32_dpp v72, v72, v72 row_shl:4 row_mask:0xf bank_mask:0xf bound_ctrl:1
	v_add_f32_dpp v67, v121, v121 row_ror:2 row_mask:0xf bank_mask:0xf bound_ctrl:1
	v_add_f32_dpp v127, v124, v124 row_shl:4 row_mask:0xf bank_mask:0xf bound_ctrl:1
	v_add_f32_dpp v124, v68, v68 row_ror:2 row_mask:0xf bank_mask:0xf bound_ctrl:1
	v_mov_b32_dpp v114, v79 row_shl:8 row_mask:0xf bank_mask:0xf bound_ctrl:1
	v_mov_b32_dpp v112, v75 row_ror:1 row_mask:0xf bank_mask:0xf bound_ctrl:1
	v_mov_b32_dpp v118, v113 row_shl:8 row_mask:0xf bank_mask:0xf bound_ctrl:1
	v_mov_b32_dpp v117, v71 row_ror:1 row_mask:0xf bank_mask:0xf bound_ctrl:1
	v_mov_b32_dpp v122, v72 row_shl:8 row_mask:0xf bank_mask:0xf bound_ctrl:1
	v_mov_b32_dpp v121, v67 row_ror:1 row_mask:0xf bank_mask:0xf bound_ctrl:1
	v_mov_b32_dpp v131, v127 row_shl:8 row_mask:0xf bank_mask:0xf bound_ctrl:1
	v_mov_b32_dpp v125, v124 row_ror:1 row_mask:0xf bank_mask:0xf bound_ctrl:1
	v_mov_b32_e32 v68, 0
	s_and_saveexec_b64 s[16:17], s[14:15]
	s_cbranch_execz .LBB0_464
	v_add_f32_e32 v127, v127, v131
	v_sub_f32_e32 v123, v123, v126
	v_add_f32_e32 v126, v126, v127
	v_add_f32_e32 v123, v123, v126
	v_add_f32_e32 v123, 0, v123
	v_add_f32_e32 v123, v111, v123
	v_mul_f32_e32 v123, 0x3fb8aa3b, v123
	v_exp_f32_e32 v123, v123
	s_nop 0
	v_cvt_pk_bf16_f32 v132, v123, s0
